# GEMM K-loops: one static s_setprio 1 for waves 4-7 before the loop instead of the per-phase priority flips (strategy 4: static priority raise for the younger wave half)
# speedup vs baseline: 1.0077x; 1.0077x over previous
.LBB0_196:
	s_ashr_i32 s9, s8, 31
	v_cmp_lt_i64_e32 vcc, s[10:11], v[140:141]
	s_lshl_b64 s[10:11], s[8:9], 20
	v_readlane_b32 s52, v254, 21
	v_readlane_b32 s53, v254, 22
	s_add_u32 s10, s52, s10
	s_addc_u32 s11, s53, s11
	s_and_b64 s[12:13], vcc, exec
	s_cselect_b32 s5, s11, s17
	s_cselect_b32 s9, s10, s16
	s_ashr_i32 s7, s6, 31
	s_lshl_b64 s[12:13], s[6:7], 20
	s_add_u32 s12, s48, s12
	s_addc_u32 s13, s49, s13
	s_and_b64 s[20:21], vcc, exec
	s_cselect_b32 s7, s13, s19
	s_cselect_b32 s15, s12, s18
	s_add_u32 s16, s16, 0x80080
	s_addc_u32 s17, s17, 0
	s_add_u32 s76, s18, 0x100
	v_mov_b32_e32 v0, 0
	s_addc_u32 s77, s19, 0
	s_mov_b32 s78, -2
	v_mov_b32_e32 v1, v0
	v_mov_b32_e32 v2, v0
	v_mov_b32_e32 v3, v0
	v_mov_b32_e32 v4, v0
	v_mov_b32_e32 v5, v0
	v_mov_b32_e32 v6, v0
	v_mov_b32_e32 v7, v0
	v_mov_b32_e32 v16, v0
	v_mov_b32_e32 v17, v0
	v_mov_b32_e32 v18, v0
	v_mov_b32_e32 v19, v0
	v_mov_b32_e32 v20, v0
	v_mov_b32_e32 v21, v0
	v_mov_b32_e32 v22, v0
	v_mov_b32_e32 v23, v0
	v_mov_b32_e32 v32, v0
	v_mov_b32_e32 v33, v0
	v_mov_b32_e32 v34, v0
	v_mov_b32_e32 v35, v0
	v_mov_b32_e32 v36, v0
	v_mov_b32_e32 v37, v0
	v_mov_b32_e32 v38, v0
	v_mov_b32_e32 v39, v0
	v_mov_b32_e32 v48, v0
	v_mov_b32_e32 v49, v0
	v_mov_b32_e32 v50, v0
	v_mov_b32_e32 v51, v0
	v_mov_b32_e32 v52, v0
	v_mov_b32_e32 v53, v0
	v_mov_b32_e32 v54, v0
	v_mov_b32_e32 v55, v0
	v_mov_b32_e32 v8, v0
	v_mov_b32_e32 v9, v0
	v_mov_b32_e32 v10, v0
	v_mov_b32_e32 v11, v0
	v_mov_b32_e32 v12, v0
	v_mov_b32_e32 v13, v0
	v_mov_b32_e32 v14, v0
	v_mov_b32_e32 v15, v0
	v_mov_b32_e32 v24, v0
	v_mov_b32_e32 v25, v0
	v_mov_b32_e32 v26, v0
	v_mov_b32_e32 v27, v0
	v_mov_b32_e32 v28, v0
	v_mov_b32_e32 v29, v0
	v_mov_b32_e32 v30, v0
	v_mov_b32_e32 v31, v0
	v_mov_b32_e32 v40, v0
	v_mov_b32_e32 v41, v0
	v_mov_b32_e32 v42, v0
	v_mov_b32_e32 v43, v0
	v_mov_b32_e32 v44, v0
	v_mov_b32_e32 v45, v0
	v_mov_b32_e32 v46, v0
	v_mov_b32_e32 v47, v0
	v_mov_b32_e32 v56, v0
	v_mov_b32_e32 v57, v0
	v_mov_b32_e32 v58, v0
	v_mov_b32_e32 v59, v0
	v_mov_b32_e32 v60, v0
	v_mov_b32_e32 v61, v0
	v_mov_b32_e32 v62, v0
	v_mov_b32_e32 v63, v0
	v_mov_b32_e32 v64, v0
	v_mov_b32_e32 v65, v0
	v_mov_b32_e32 v66, v0
	v_mov_b32_e32 v67, v0
	v_mov_b32_e32 v68, v0
	v_mov_b32_e32 v69, v0
	v_mov_b32_e32 v70, v0
	v_mov_b32_e32 v71, v0
	v_mov_b32_e32 v80, v0
	v_mov_b32_e32 v81, v0
	v_mov_b32_e32 v82, v0
	v_mov_b32_e32 v83, v0
	v_mov_b32_e32 v84, v0
	v_mov_b32_e32 v85, v0
	v_mov_b32_e32 v86, v0
	v_mov_b32_e32 v87, v0
	v_mov_b32_e32 v96, v0
	v_mov_b32_e32 v97, v0
	v_mov_b32_e32 v98, v0
	v_mov_b32_e32 v99, v0
	v_mov_b32_e32 v100, v0
	v_mov_b32_e32 v101, v0
	v_mov_b32_e32 v102, v0
	v_mov_b32_e32 v103, v0
	v_mov_b32_e32 v112, v0
	v_mov_b32_e32 v113, v0
	v_mov_b32_e32 v114, v0
	v_mov_b32_e32 v115, v0
	v_mov_b32_e32 v116, v0
	v_mov_b32_e32 v117, v0
	v_mov_b32_e32 v118, v0
	v_mov_b32_e32 v119, v0
	v_mov_b32_e32 v72, v0
	v_mov_b32_e32 v73, v0
	v_mov_b32_e32 v74, v0
	v_mov_b32_e32 v75, v0
	v_mov_b32_e32 v76, v0
	v_mov_b32_e32 v77, v0
	v_mov_b32_e32 v78, v0
	v_mov_b32_e32 v79, v0
	v_mov_b32_e32 v88, v0
	v_mov_b32_e32 v89, v0
	v_mov_b32_e32 v90, v0
	v_mov_b32_e32 v91, v0
	v_mov_b32_e32 v92, v0
	v_mov_b32_e32 v93, v0
	v_mov_b32_e32 v94, v0
	v_mov_b32_e32 v95, v0
	v_mov_b32_e32 v104, v0
	v_mov_b32_e32 v105, v0
	v_mov_b32_e32 v106, v0
	v_mov_b32_e32 v107, v0
	v_mov_b32_e32 v108, v0
	v_mov_b32_e32 v109, v0
	v_mov_b32_e32 v110, v0
	v_mov_b32_e32 v111, v0
	v_mov_b32_e32 v120, v0
	v_mov_b32_e32 v121, v0
	v_mov_b32_e32 v122, v0
	v_mov_b32_e32 v123, v0
	v_mov_b32_e32 v124, v0
	v_mov_b32_e32 v125, v0
	v_mov_b32_e32 v126, v0
	v_mov_b32_e32 v127, v0
	v_readlane_b32 s54, v254, 23
	v_readlane_b32 s55, v254, 24
	v_readlane_b32 s56, v254, 25
	v_readlane_b32 s57, v254, 26
	v_readlane_b32 s58, v254, 27
	v_readlane_b32 s59, v254, 28
	v_readlane_b32 s60, v254, 29
	v_readlane_b32 s61, v254, 30
	v_readlane_b32 s62, v254, 31
	v_readlane_b32 s63, v254, 32
	v_readlane_b32 s64, v254, 33
	v_readlane_b32 s65, v254, 34
	v_readlane_b32 s66, v254, 35
	v_readlane_b32 s67, v254, 36
	s_cmpk_gt_u32 s22, 0xff
	s_cbranch_scc0 .Lprio_k0
	s_setprio 1
.Lprio_k0:
.LBB0_197:
	ds_read_b128 v[144:147], v151
	ds_read_b128 v[154:157], v151 offset:1024
	ds_read_b128 v[158:161], v151 offset:2048
	ds_read_b128 v[162:165], v151 offset:3072
	s_add_u32 s18, s16, 0xfff80080
	s_addc_u32 s19, s17, -1
	s_cmp_eq_u32 s78, 28
	s_cselect_b32 s21, s5, s19
	s_cselect_b32 s20, s9, s18
	s_cselect_b32 s19, s7, s77
	s_cselect_b32 s18, s15, s76
	v_lshl_add_u64 v[198:199], s[16:17], 0, v[136:137]
	s_add_i32 m0, s24, 0xc000
	ds_read_b128 v[166:169], v152
	ds_read_b128 v[170:173], v152 offset:1024
	ds_read_b128 v[174:177], v152 offset:2048
	ds_read_b128 v[178:181], v152 offset:3072
	ds_read_b128 v[182:185], v152 offset:4096
	ds_read_b128 v[186:189], v152 offset:5120
	ds_read_b128 v[190:193], v152 offset:6144
	ds_read_b128 v[194:197], v152 offset:7168
	global_load_lds_dwordx4 v[198:199], off
	v_lshl_add_u64 v[198:199], s[16:17], 0, v[138:139]
	s_add_i32 m0, s24, 0xe000
	s_nop 0
	global_load_lds_dwordx4 v[198:199], off
	s_waitcnt lgkmcnt(8)
	s_barrier
	s_waitcnt lgkmcnt(0)
	s_waitcnt lgkmcnt(0)
	v_mfma_f32_16x16x32_f16 v[124:127], v[144:147], v[166:169], v[124:127]
	v_mfma_f32_16x16x32_f16 v[120:123], v[158:161], v[166:169], v[120:123]
	v_mfma_f32_16x16x32_f16 v[108:111], v[144:147], v[174:177], v[108:111]
	v_mfma_f32_16x16x32_f16 v[104:107], v[158:161], v[174:177], v[104:107]
	v_mfma_f32_16x16x32_f16 v[92:95], v[144:147], v[182:185], v[92:95]
	v_mfma_f32_16x16x32_f16 v[88:91], v[158:161], v[182:185], v[88:91]
	v_mfma_f32_16x16x32_f16 v[76:79], v[144:147], v[190:193], v[76:79]
	v_mfma_f32_16x16x32_f16 v[72:75], v[158:161], v[190:193], v[72:75]
	v_mfma_f32_16x16x32_f16 v[124:127], v[154:157], v[170:173], v[124:127]
	v_mfma_f32_16x16x32_f16 v[120:123], v[162:165], v[170:173], v[120:123]
	v_mfma_f32_16x16x32_f16 v[108:111], v[154:157], v[178:181], v[108:111]
	v_mfma_f32_16x16x32_f16 v[104:107], v[162:165], v[178:181], v[104:107]
	v_mfma_f32_16x16x32_f16 v[92:95], v[154:157], v[186:189], v[92:95]
	v_mfma_f32_16x16x32_f16 v[88:91], v[162:165], v[186:189], v[88:91]
	v_mfma_f32_16x16x32_f16 v[76:79], v[154:157], v[194:197], v[76:79]
	v_mfma_f32_16x16x32_f16 v[72:75], v[162:165], v[194:197], v[72:75]
	s_barrier
	s_add_i32 s79, s68, s23
	v_lshl_add_u64 v[214:215], s[18:19], 0, v[130:131]
	s_mov_b32 m0, s79
	ds_read_b128 v[198:201], v153
	ds_read_b128 v[202:205], v153 offset:1024
	ds_read_b128 v[206:209], v153 offset:2048
	ds_read_b128 v[210:213], v153 offset:3072
	global_load_lds_dwordx4 v[214:215], off
	v_lshl_add_u64 v[216:217], s[18:19], 0, v[134:135]
	s_add_i32 m0, s79, 0x2000
	s_nop 0
	global_load_lds_dwordx4 v[216:217], off
	s_barrier
	s_waitcnt lgkmcnt(0)
	s_waitcnt lgkmcnt(0)
	v_mfma_f32_16x16x32_f16 v[116:119], v[198:201], v[166:169], v[116:119]
	v_mfma_f32_16x16x32_f16 v[112:115], v[206:209], v[166:169], v[112:115]
	v_mfma_f32_16x16x32_f16 v[100:103], v[198:201], v[174:177], v[100:103]
	v_mfma_f32_16x16x32_f16 v[96:99], v[206:209], v[174:177], v[96:99]
	v_mfma_f32_16x16x32_f16 v[84:87], v[198:201], v[182:185], v[84:87]
	v_mfma_f32_16x16x32_f16 v[80:83], v[206:209], v[182:185], v[80:83]
	v_mfma_f32_16x16x32_f16 v[68:71], v[198:201], v[190:193], v[68:71]
	v_mfma_f32_16x16x32_f16 v[64:67], v[206:209], v[190:193], v[64:67]
	v_mfma_f32_16x16x32_f16 v[116:119], v[202:205], v[170:173], v[116:119]
	v_mfma_f32_16x16x32_f16 v[112:115], v[210:213], v[170:173], v[112:115]
	v_mfma_f32_16x16x32_f16 v[100:103], v[202:205], v[178:181], v[100:103]
	v_mfma_f32_16x16x32_f16 v[96:99], v[210:213], v[178:181], v[96:99]
	v_mfma_f32_16x16x32_f16 v[84:87], v[202:205], v[186:189], v[84:87]
	v_mfma_f32_16x16x32_f16 v[80:83], v[210:213], v[186:189], v[80:83]
	v_mfma_f32_16x16x32_f16 v[68:71], v[202:205], v[194:197], v[68:71]
	v_mfma_f32_16x16x32_f16 v[64:67], v[210:213], v[194:197], v[64:67]
	s_mov_b32 m0, s24
	v_lshl_add_u64 v[218:219], s[20:21], 0, v[128:129]
	s_barrier
	ds_read_b128 v[166:169], v152 offset:16384
	ds_read_b128 v[170:173], v152 offset:17408
	ds_read_b128 v[174:177], v152 offset:18432
	ds_read_b128 v[178:181], v152 offset:19456
	ds_read_b128 v[182:185], v152 offset:20480
	ds_read_b128 v[186:189], v152 offset:21504
	ds_read_b128 v[190:193], v152 offset:22528
	ds_read_b128 v[194:197], v152 offset:23552
	global_load_lds_dwordx4 v[218:219], off
	v_lshl_add_u64 v[220:221], s[20:21], 0, v[132:133]
	s_mov_b32 m0, s25
	s_nop 0
	global_load_lds_dwordx4 v[220:221], off
	s_barrier
	s_waitcnt lgkmcnt(0)
	s_waitcnt lgkmcnt(0)
	v_mfma_f32_16x16x32_f16 v[60:63], v[144:147], v[166:169], v[60:63]
	v_mfma_f32_16x16x32_f16 v[56:59], v[158:161], v[166:169], v[56:59]
	v_mfma_f32_16x16x32_f16 v[44:47], v[144:147], v[174:177], v[44:47]
	v_mfma_f32_16x16x32_f16 v[40:43], v[158:161], v[174:177], v[40:43]
	v_mfma_f32_16x16x32_f16 v[28:31], v[144:147], v[182:185], v[28:31]
	v_mfma_f32_16x16x32_f16 v[24:27], v[158:161], v[182:185], v[24:27]
	v_mfma_f32_16x16x32_f16 v[12:15], v[144:147], v[190:193], v[12:15]
	v_mfma_f32_16x16x32_f16 v[8:11], v[158:161], v[190:193], v[8:11]
	v_mfma_f32_16x16x32_f16 v[60:63], v[154:157], v[170:173], v[60:63]
	v_mfma_f32_16x16x32_f16 v[56:59], v[162:165], v[170:173], v[56:59]
	v_mfma_f32_16x16x32_f16 v[44:47], v[154:157], v[178:181], v[44:47]
	v_mfma_f32_16x16x32_f16 v[40:43], v[162:165], v[178:181], v[40:43]
	v_mfma_f32_16x16x32_f16 v[28:31], v[154:157], v[186:189], v[28:31]
	v_mfma_f32_16x16x32_f16 v[24:27], v[162:165], v[186:189], v[24:27]
	v_mfma_f32_16x16x32_f16 v[12:15], v[154:157], v[194:197], v[12:15]
	v_mfma_f32_16x16x32_f16 v[8:11], v[162:165], v[194:197], v[8:11]
	s_barrier
	s_add_u32 s80, s18, 0x80000
	s_addc_u32 s81, s19, 0
	s_add_i32 s79, s69, s23
	v_lshl_add_u64 v[144:145], s[80:81], 0, v[130:131]
	s_mov_b32 m0, s79
	s_nop 0
	global_load_lds_dwordx4 v[144:145], off
	v_lshl_add_u64 v[144:145], s[80:81], 0, v[134:135]
	s_add_i32 m0, s79, 0x2000
	s_nop 0
	global_load_lds_dwordx4 v[144:145], off
	s_waitcnt vmcnt(6)
	s_barrier
	v_mfma_f32_16x16x32_f16 v[52:55], v[198:201], v[166:169], v[52:55]
	v_mfma_f32_16x16x32_f16 v[48:51], v[206:209], v[166:169], v[48:51]
	v_mfma_f32_16x16x32_f16 v[36:39], v[198:201], v[174:177], v[36:39]
	v_mfma_f32_16x16x32_f16 v[32:35], v[206:209], v[174:177], v[32:35]
	v_mfma_f32_16x16x32_f16 v[20:23], v[198:201], v[182:185], v[20:23]
	v_mfma_f32_16x16x32_f16 v[16:19], v[206:209], v[182:185], v[16:19]
	v_mfma_f32_16x16x32_f16 v[4:7], v[198:201], v[190:193], v[4:7]
	v_mfma_f32_16x16x32_f16 v[0:3], v[206:209], v[190:193], v[0:3]
	v_mfma_f32_16x16x32_f16 v[52:55], v[202:205], v[170:173], v[52:55]
	v_mfma_f32_16x16x32_f16 v[48:51], v[210:213], v[170:173], v[48:51]
	v_mfma_f32_16x16x32_f16 v[36:39], v[202:205], v[178:181], v[36:39]
	v_mfma_f32_16x16x32_f16 v[32:35], v[210:213], v[178:181], v[32:35]
	v_mfma_f32_16x16x32_f16 v[20:23], v[202:205], v[186:189], v[20:23]
	v_mfma_f32_16x16x32_f16 v[16:19], v[210:213], v[186:189], v[16:19]
	v_mfma_f32_16x16x32_f16 v[4:7], v[202:205], v[194:197], v[4:7]
	v_mfma_f32_16x16x32_f16 v[0:3], v[210:213], v[194:197], v[0:3]
	s_add_i32 s79, 0, 0x18000
	v_add_u32_e32 v162, s79, v149
	s_barrier
	ds_read_b128 v[144:147], v162
	ds_read_b128 v[154:157], v162 offset:1024
	ds_read_b128 v[158:161], v162 offset:2048
	ds_read_b128 v[162:165], v162 offset:3072
	s_add_u32 s20, s20, 0x80000
	s_addc_u32 s21, s21, 0
	s_mov_b32 m0, s26
	v_lshl_add_u64 v[198:199], s[20:21], 0, v[128:129]
	ds_read_b128 v[166:169], v152 offset:32768
	ds_read_b128 v[170:173], v152 offset:33792
	ds_read_b128 v[174:177], v152 offset:34816
	ds_read_b128 v[178:181], v152 offset:35840
	ds_read_b128 v[182:185], v152 offset:36864
	ds_read_b128 v[186:189], v152 offset:37888
	ds_read_b128 v[190:193], v152 offset:38912
	ds_read_b128 v[194:197], v152 offset:39936
	global_load_lds_dwordx4 v[198:199], off
	v_lshl_add_u64 v[198:199], s[20:21], 0, v[132:133]
	s_mov_b32 m0, s27
	s_nop 0
	global_load_lds_dwordx4 v[198:199], off
	s_waitcnt lgkmcnt(8)
	s_barrier
	s_waitcnt lgkmcnt(0)
	s_waitcnt lgkmcnt(0)
	v_mfma_f32_16x16x32_f16 v[124:127], v[144:147], v[166:169], v[124:127]
	v_mfma_f32_16x16x32_f16 v[120:123], v[158:161], v[166:169], v[120:123]
	v_mfma_f32_16x16x32_f16 v[108:111], v[144:147], v[174:177], v[108:111]
	v_mfma_f32_16x16x32_f16 v[104:107], v[158:161], v[174:177], v[104:107]
	v_mfma_f32_16x16x32_f16 v[92:95], v[144:147], v[182:185], v[92:95]
	v_mfma_f32_16x16x32_f16 v[88:91], v[158:161], v[182:185], v[88:91]
	v_mfma_f32_16x16x32_f16 v[76:79], v[144:147], v[190:193], v[76:79]
	v_mfma_f32_16x16x32_f16 v[72:75], v[158:161], v[190:193], v[72:75]
	v_mfma_f32_16x16x32_f16 v[124:127], v[154:157], v[170:173], v[124:127]
	v_mfma_f32_16x16x32_f16 v[120:123], v[162:165], v[170:173], v[120:123]
	v_mfma_f32_16x16x32_f16 v[108:111], v[154:157], v[178:181], v[108:111]
	v_mfma_f32_16x16x32_f16 v[104:107], v[162:165], v[178:181], v[104:107]
	v_mfma_f32_16x16x32_f16 v[92:95], v[154:157], v[186:189], v[92:95]
	v_mfma_f32_16x16x32_f16 v[88:91], v[162:165], v[186:189], v[88:91]
	v_mfma_f32_16x16x32_f16 v[76:79], v[154:157], v[194:197], v[76:79]
	v_mfma_f32_16x16x32_f16 v[72:75], v[162:165], v[194:197], v[72:75]
	s_barrier
	s_add_i32 s20, 0, 0x1c000
	s_add_i32 s21, s79, s23
	v_add_u32_e32 v210, s20, v149
	v_lshl_add_u64 v[214:215], v[214:215], 0, s[0:1]
	s_mov_b32 m0, s21
	ds_read_b128 v[198:201], v210
	ds_read_b128 v[202:205], v210 offset:1024
	ds_read_b128 v[206:209], v210 offset:2048
	ds_read_b128 v[210:213], v210 offset:3072
	global_load_lds_dwordx4 v[214:215], off
	v_lshl_add_u64 v[214:215], v[216:217], 0, s[0:1]
	s_add_i32 m0, s21, 0x2000
	s_nop 0
	global_load_lds_dwordx4 v[214:215], off
	s_barrier
	s_waitcnt lgkmcnt(0)
	s_waitcnt lgkmcnt(0)
	v_mfma_f32_16x16x32_f16 v[116:119], v[198:201], v[166:169], v[116:119]
	v_mfma_f32_16x16x32_f16 v[112:115], v[206:209], v[166:169], v[112:115]
	v_mfma_f32_16x16x32_f16 v[100:103], v[198:201], v[174:177], v[100:103]
	v_mfma_f32_16x16x32_f16 v[96:99], v[206:209], v[174:177], v[96:99]
	v_mfma_f32_16x16x32_f16 v[84:87], v[198:201], v[182:185], v[84:87]
	v_mfma_f32_16x16x32_f16 v[80:83], v[206:209], v[182:185], v[80:83]
	v_mfma_f32_16x16x32_f16 v[68:71], v[198:201], v[190:193], v[68:71]
	v_mfma_f32_16x16x32_f16 v[64:67], v[206:209], v[190:193], v[64:67]
	v_mfma_f32_16x16x32_f16 v[116:119], v[202:205], v[170:173], v[116:119]
	v_mfma_f32_16x16x32_f16 v[112:115], v[210:213], v[170:173], v[112:115]
	v_mfma_f32_16x16x32_f16 v[100:103], v[202:205], v[178:181], v[100:103]
	v_mfma_f32_16x16x32_f16 v[96:99], v[210:213], v[178:181], v[96:99]
	v_mfma_f32_16x16x32_f16 v[84:87], v[202:205], v[186:189], v[84:87]
	v_mfma_f32_16x16x32_f16 v[80:83], v[210:213], v[186:189], v[80:83]
	v_mfma_f32_16x16x32_f16 v[68:71], v[202:205], v[194:197], v[68:71]
	v_mfma_f32_16x16x32_f16 v[64:67], v[210:213], v[194:197], v[64:67]
	s_mov_b32 m0, s29
	v_lshl_add_u64 v[214:215], v[218:219], 0, s[0:1]
	s_barrier
	ds_read_b128 v[166:169], v152 offset:49152
	ds_read_b128 v[170:173], v152 offset:50176
	ds_read_b128 v[174:177], v152 offset:51200
	ds_read_b128 v[178:181], v152 offset:52224
	ds_read_b128 v[182:185], v152 offset:53248
	ds_read_b128 v[186:189], v152 offset:54272
	ds_read_b128 v[190:193], v152 offset:55296
	ds_read_b128 v[194:197], v152 offset:56320
	global_load_lds_dwordx4 v[214:215], off
	v_lshl_add_u64 v[214:215], v[220:221], 0, s[0:1]
	s_mov_b32 m0, s30
	s_nop 0
	global_load_lds_dwordx4 v[214:215], off
	s_barrier
	s_waitcnt lgkmcnt(0)
	s_waitcnt lgkmcnt(0)
	v_mfma_f32_16x16x32_f16 v[60:63], v[144:147], v[166:169], v[60:63]
	v_mfma_f32_16x16x32_f16 v[56:59], v[158:161], v[166:169], v[56:59]
	v_mfma_f32_16x16x32_f16 v[44:47], v[144:147], v[174:177], v[44:47]
	v_mfma_f32_16x16x32_f16 v[40:43], v[158:161], v[174:177], v[40:43]
	v_mfma_f32_16x16x32_f16 v[28:31], v[144:147], v[182:185], v[28:31]
	v_mfma_f32_16x16x32_f16 v[24:27], v[158:161], v[182:185], v[24:27]
	v_mfma_f32_16x16x32_f16 v[12:15], v[144:147], v[190:193], v[12:15]
	v_mfma_f32_16x16x32_f16 v[8:11], v[158:161], v[190:193], v[8:11]
	v_mfma_f32_16x16x32_f16 v[60:63], v[154:157], v[170:173], v[60:63]
	v_mfma_f32_16x16x32_f16 v[56:59], v[162:165], v[170:173], v[56:59]
	v_mfma_f32_16x16x32_f16 v[44:47], v[154:157], v[178:181], v[44:47]
	v_mfma_f32_16x16x32_f16 v[40:43], v[162:165], v[178:181], v[40:43]
	v_mfma_f32_16x16x32_f16 v[28:31], v[154:157], v[186:189], v[28:31]
	v_mfma_f32_16x16x32_f16 v[24:27], v[162:165], v[186:189], v[24:27]
	v_mfma_f32_16x16x32_f16 v[12:15], v[154:157], v[194:197], v[12:15]
	v_mfma_f32_16x16x32_f16 v[8:11], v[162:165], v[194:197], v[8:11]
	s_barrier
	s_add_u32 s18, s18, 0x80080
	s_addc_u32 s19, s19, 0
	s_add_i32 s20, s20, s23
	v_lshl_add_u64 v[144:145], s[18:19], 0, v[130:131]
	s_mov_b32 m0, s20
	s_nop 0
	global_load_lds_dwordx4 v[144:145], off
	v_lshl_add_u64 v[144:145], s[18:19], 0, v[134:135]
	s_add_i32 m0, s20, 0x2000
	s_nop 0
	global_load_lds_dwordx4 v[144:145], off
	s_waitcnt vmcnt(6)
	s_barrier
	v_mfma_f32_16x16x32_f16 v[52:55], v[198:201], v[166:169], v[52:55]
	v_mfma_f32_16x16x32_f16 v[48:51], v[206:209], v[166:169], v[48:51]
	v_mfma_f32_16x16x32_f16 v[36:39], v[198:201], v[174:177], v[36:39]
	v_mfma_f32_16x16x32_f16 v[32:35], v[206:209], v[174:177], v[32:35]
	v_mfma_f32_16x16x32_f16 v[20:23], v[198:201], v[182:185], v[20:23]
	v_mfma_f32_16x16x32_f16 v[16:19], v[206:209], v[182:185], v[16:19]
	v_mfma_f32_16x16x32_f16 v[4:7], v[198:201], v[190:193], v[4:7]
	v_mfma_f32_16x16x32_f16 v[0:3], v[206:209], v[190:193], v[0:3]
	v_mfma_f32_16x16x32_f16 v[52:55], v[202:205], v[170:173], v[52:55]
	v_mfma_f32_16x16x32_f16 v[48:51], v[210:213], v[170:173], v[48:51]
	v_mfma_f32_16x16x32_f16 v[36:39], v[202:205], v[178:181], v[36:39]
	v_mfma_f32_16x16x32_f16 v[32:35], v[210:213], v[178:181], v[32:35]
	v_mfma_f32_16x16x32_f16 v[20:23], v[202:205], v[186:189], v[20:23]
	v_mfma_f32_16x16x32_f16 v[16:19], v[210:213], v[186:189], v[16:19]
	v_mfma_f32_16x16x32_f16 v[4:7], v[202:205], v[194:197], v[4:7]
	v_mfma_f32_16x16x32_f16 v[0:3], v[210:213], v[194:197], v[0:3]
	s_add_i32 s78, s78, 2
	s_add_u32 s16, s16, 0x100
	s_addc_u32 s17, s17, 0
	s_add_u32 s76, s76, 0x100
	s_addc_u32 s77, s77, 0
	s_cmp_gt_u32 s78, 29
	s_barrier
	s_cbranch_scc0 .LBB0_197
	s_setprio 0
	v_readlane_b32 s52, v254, 21
	v_readlane_b32 s54, v254, 23
	v_readlane_b32 s55, v254, 24
	v_lshl_add_u32 v154, s14, 8, v148
	v_lshl_or_b32 v144, s4, 8, v150
	v_mov_b64_e32 v[146:147], s[54:55]
	v_mad_i64_i32 v[146:147], s[4:5], v154, s70, v[146:147]
	v_cmp_gt_i32_e32 vcc, s71, v144
	v_ashrrev_i32_e32 v145, 31, v144
	v_readlane_b32 s53, v254, 22
	v_readlane_b32 s56, v254, 25
	v_readlane_b32 s57, v254, 26
	v_readlane_b32 s58, v254, 27
	v_readlane_b32 s59, v254, 28
	v_readlane_b32 s60, v254, 29
	v_readlane_b32 s61, v254, 30
	v_readlane_b32 s62, v254, 31
	v_readlane_b32 s63, v254, 32
	v_readlane_b32 s64, v254, 33
	v_readlane_b32 s65, v254, 34
	v_readlane_b32 s66, v254, 35
	v_readlane_b32 s67, v254, 36
	s_and_saveexec_b64 s[4:5], vcc
	s_cbranch_execz .LBB0_200
	v_cvt_pk_f16_f32 v123, v122, v123
	v_cvt_pk_f16_f32 v122, v120, v121
	v_cvt_pk_f16_f32 v121, v126, v127
	v_cvt_pk_f16_f32 v120, v124, v125
	v_lshl_add_u64 v[124:125], v[144:145], 1, v[146:147]
	global_store_dwordx4 v[124:125], v[120:123], off

.LBB0_646:
	s_ashr_i32 s9, s8, 31
	v_cmp_lt_i64_e32 vcc, s[10:11], v[216:217]
	s_lshl_b64 s[10:11], s[8:9], 20
	v_readlane_b32 s52, v254, 21
	v_readlane_b32 s53, v254, 22
	s_add_u32 s10, s52, s10
	s_addc_u32 s11, s53, s11
	s_and_b64 s[12:13], vcc, exec
	s_cselect_b32 s9, s11, s17
	s_cselect_b32 s31, s10, s16
	s_ashr_i32 s7, s6, 31
	s_lshl_b64 s[12:13], s[6:7], 20
	s_add_u32 s12, s50, s12
	s_addc_u32 s13, s51, s13
	s_and_b64 s[20:21], vcc, exec
	s_cselect_b32 s7, s13, s19
	s_cselect_b32 s77, s12, s18
	s_add_u32 s16, s16, 0x80080
	s_addc_u32 s17, s17, 0
	s_add_u32 s78, s18, 0x100
	v_mov_b32_e32 v0, 0
	s_addc_u32 s79, s19, 0
	s_mov_b32 s80, -2
	v_mov_b32_e32 v1, v0
	v_mov_b32_e32 v2, v0
	v_mov_b32_e32 v3, v0
	v_mov_b32_e32 v4, v0
	v_mov_b32_e32 v5, v0
	v_mov_b32_e32 v6, v0
	v_mov_b32_e32 v7, v0
	v_mov_b32_e32 v16, v0
	v_mov_b32_e32 v17, v0
	v_mov_b32_e32 v18, v0
	v_mov_b32_e32 v19, v0
	v_mov_b32_e32 v20, v0
	v_mov_b32_e32 v21, v0
	v_mov_b32_e32 v22, v0
	v_mov_b32_e32 v23, v0
	v_mov_b32_e32 v32, v0
	v_mov_b32_e32 v33, v0
	v_mov_b32_e32 v34, v0
	v_mov_b32_e32 v35, v0
	v_mov_b32_e32 v36, v0
	v_mov_b32_e32 v37, v0
	v_mov_b32_e32 v38, v0
	v_mov_b32_e32 v39, v0
	v_mov_b32_e32 v48, v0
	v_mov_b32_e32 v49, v0
	v_mov_b32_e32 v50, v0
	v_mov_b32_e32 v51, v0
	v_mov_b32_e32 v52, v0
	v_mov_b32_e32 v53, v0
	v_mov_b32_e32 v54, v0
	v_mov_b32_e32 v55, v0
	v_mov_b32_e32 v8, v0
	v_mov_b32_e32 v9, v0
	v_mov_b32_e32 v10, v0
	v_mov_b32_e32 v11, v0
	v_mov_b32_e32 v12, v0
	v_mov_b32_e32 v13, v0
	v_mov_b32_e32 v14, v0
	v_mov_b32_e32 v15, v0
	v_mov_b32_e32 v24, v0
	v_mov_b32_e32 v25, v0
	v_mov_b32_e32 v26, v0
	v_mov_b32_e32 v27, v0
	v_mov_b32_e32 v28, v0
	v_mov_b32_e32 v29, v0
	v_mov_b32_e32 v30, v0
	v_mov_b32_e32 v31, v0
	v_mov_b32_e32 v40, v0
	v_mov_b32_e32 v41, v0
	v_mov_b32_e32 v42, v0
	v_mov_b32_e32 v43, v0
	v_mov_b32_e32 v44, v0
	v_mov_b32_e32 v45, v0
	v_mov_b32_e32 v46, v0
	v_mov_b32_e32 v47, v0
	v_mov_b32_e32 v56, v0
	v_mov_b32_e32 v57, v0
	v_mov_b32_e32 v58, v0
	v_mov_b32_e32 v59, v0
	v_mov_b32_e32 v60, v0
	v_mov_b32_e32 v61, v0
	v_mov_b32_e32 v62, v0
	v_mov_b32_e32 v63, v0
	v_mov_b32_e32 v64, v0
	v_mov_b32_e32 v65, v0
	v_mov_b32_e32 v66, v0
	v_mov_b32_e32 v67, v0
	v_mov_b32_e32 v68, v0
	v_mov_b32_e32 v69, v0
	v_mov_b32_e32 v70, v0
	v_mov_b32_e32 v71, v0
	v_mov_b32_e32 v84, v0
	v_mov_b32_e32 v85, v0
	v_mov_b32_e32 v86, v0
	v_mov_b32_e32 v87, v0
	v_mov_b32_e32 v92, v0
	v_mov_b32_e32 v93, v0
	v_mov_b32_e32 v94, v0
	v_mov_b32_e32 v95, v0
	v_mov_b32_e32 v112, v0
	v_mov_b32_e32 v113, v0
	v_mov_b32_e32 v114, v0
	v_mov_b32_e32 v115, v0
	v_mov_b32_e32 v116, v0
	v_mov_b32_e32 v117, v0
	v_mov_b32_e32 v118, v0
	v_mov_b32_e32 v119, v0
	v_mov_b32_e32 v140, v0
	v_mov_b32_e32 v141, v0
	v_mov_b32_e32 v142, v0
	v_mov_b32_e32 v143, v0
	v_mov_b32_e32 v144, v0
	v_mov_b32_e32 v145, v0
	v_mov_b32_e32 v146, v0
	v_mov_b32_e32 v147, v0
	v_mov_b32_e32 v72, v0
	v_mov_b32_e32 v73, v0
	v_mov_b32_e32 v74, v0
	v_mov_b32_e32 v75, v0
	v_mov_b32_e32 v76, v0
	v_mov_b32_e32 v77, v0
	v_mov_b32_e32 v78, v0
	v_mov_b32_e32 v79, v0
	v_mov_b32_e32 v104, v0
	v_mov_b32_e32 v105, v0
	v_mov_b32_e32 v106, v0
	v_mov_b32_e32 v107, v0
	v_mov_b32_e32 v108, v0
	v_mov_b32_e32 v109, v0
	v_mov_b32_e32 v110, v0
	v_mov_b32_e32 v111, v0
	v_mov_b32_e32 v124, v0
	v_mov_b32_e32 v125, v0
	v_mov_b32_e32 v126, v0
	v_mov_b32_e32 v127, v0
	v_mov_b32_e32 v128, v0
	v_mov_b32_e32 v129, v0
	v_mov_b32_e32 v130, v0
	v_mov_b32_e32 v131, v0
	v_mov_b32_e32 v164, v0
	v_mov_b32_e32 v165, v0
	v_mov_b32_e32 v166, v0
	v_mov_b32_e32 v167, v0
	v_mov_b32_e32 v168, v0
	v_mov_b32_e32 v169, v0
	v_mov_b32_e32 v170, v0
	v_mov_b32_e32 v171, v0
	v_readlane_b32 s54, v254, 23
	v_readlane_b32 s55, v254, 24
	v_readlane_b32 s56, v254, 25
	v_readlane_b32 s57, v254, 26
	v_readlane_b32 s58, v254, 27
	v_readlane_b32 s59, v254, 28
	v_readlane_b32 s60, v254, 29
	v_readlane_b32 s61, v254, 30
	v_readlane_b32 s62, v254, 31
	v_readlane_b32 s63, v254, 32
	v_readlane_b32 s64, v254, 33
	v_readlane_b32 s65, v254, 34
	v_readlane_b32 s66, v254, 35
	v_readlane_b32 s67, v254, 36
	s_cmpk_gt_u32 s22, 0xff
	s_cbranch_scc0 .Lprio_k1
	s_setprio 1
.Lprio_k1:
.LBB0_647:
	ds_read_b128 v[80:83], v243
	ds_read_b128 v[88:91], v243 offset:1024
	ds_read_b128 v[96:99], v243 offset:2048
	ds_read_b128 v[100:103], v243 offset:3072
	s_add_u32 s18, s16, 0xfff80080
	s_addc_u32 s19, s17, -1
	s_cmp_eq_u32 s80, 28
	s_cselect_b32 s21, s9, s19
	s_cselect_b32 s20, s31, s18
	s_cselect_b32 s19, s7, s79
	s_cselect_b32 s18, s77, s78
	v_lshl_add_u64 v[176:177], s[16:17], 0, v[212:213]
	s_add_i32 m0, s15, 0xc000
	ds_read_b128 v[120:123], v244
	ds_read_b128 v[132:135], v244 offset:1024
	ds_read_b128 v[136:139], v244 offset:2048
	ds_read_b128 v[148:151], v244 offset:3072
	ds_read_b128 v[152:155], v244 offset:4096
	ds_read_b128 v[156:159], v244 offset:5120
	ds_read_b128 v[160:163], v244 offset:6144
	ds_read_b128 v[172:175], v244 offset:7168
	global_load_lds_dwordx4 v[176:177], off
	v_lshl_add_u64 v[176:177], s[16:17], 0, v[214:215]
	s_add_i32 m0, s15, 0xe000
	s_nop 0
	global_load_lds_dwordx4 v[176:177], off
	s_waitcnt lgkmcnt(8)
	s_barrier
	s_waitcnt lgkmcnt(0)
	s_waitcnt lgkmcnt(0)
	v_mfma_f32_16x16x32_f16 v[168:171], v[80:83], v[120:123], v[168:171]
	v_mfma_f32_16x16x32_f16 v[164:167], v[96:99], v[120:123], v[164:167]
	v_mfma_f32_16x16x32_f16 v[128:131], v[80:83], v[136:139], v[128:131]
	v_mfma_f32_16x16x32_f16 v[124:127], v[96:99], v[136:139], v[124:127]
	v_mfma_f32_16x16x32_f16 v[108:111], v[80:83], v[152:155], v[108:111]
	v_mfma_f32_16x16x32_f16 v[104:107], v[96:99], v[152:155], v[104:107]
	v_mfma_f32_16x16x32_f16 v[76:79], v[80:83], v[160:163], v[76:79]
	v_mfma_f32_16x16x32_f16 v[72:75], v[96:99], v[160:163], v[72:75]
	v_mfma_f32_16x16x32_f16 v[168:171], v[88:91], v[132:135], v[168:171]
	v_mfma_f32_16x16x32_f16 v[164:167], v[100:103], v[132:135], v[164:167]
	v_mfma_f32_16x16x32_f16 v[128:131], v[88:91], v[148:151], v[128:131]
	v_mfma_f32_16x16x32_f16 v[124:127], v[100:103], v[148:151], v[124:127]
	v_mfma_f32_16x16x32_f16 v[108:111], v[88:91], v[156:159], v[108:111]
	v_mfma_f32_16x16x32_f16 v[104:107], v[100:103], v[156:159], v[104:107]
	v_mfma_f32_16x16x32_f16 v[76:79], v[88:91], v[172:175], v[76:79]
	v_mfma_f32_16x16x32_f16 v[72:75], v[100:103], v[172:175], v[72:75]
	s_barrier
	s_add_i32 s81, s71, s24
	v_lshl_add_u64 v[196:197], s[18:19], 0, v[206:207]
	s_mov_b32 m0, s81
	ds_read_b128 v[176:179], v245
	ds_read_b128 v[180:183], v245 offset:1024
	ds_read_b128 v[184:187], v245 offset:2048
	ds_read_b128 v[188:191], v245 offset:3072
	global_load_lds_dwordx4 v[196:197], off
	v_lshl_add_u64 v[198:199], s[18:19], 0, v[210:211]
	s_add_i32 m0, s81, 0x2000
	s_nop 0
	global_load_lds_dwordx4 v[198:199], off
	s_barrier
	s_waitcnt lgkmcnt(0)
	s_waitcnt lgkmcnt(0)
	v_mfma_f32_16x16x32_f16 v[144:147], v[176:179], v[120:123], v[144:147]
	v_mfma_f32_16x16x32_f16 v[116:119], v[176:179], v[136:139], v[116:119]
	v_mfma_f32_16x16x32_f16 v[112:115], v[184:187], v[136:139], v[112:115]
	v_mfma_f32_16x16x32_f16 v[92:95], v[176:179], v[152:155], v[92:95]
	v_mfma_f32_16x16x32_f16 v[84:87], v[184:187], v[152:155], v[84:87]
	v_mfma_f32_16x16x32_f16 v[68:71], v[176:179], v[160:163], v[68:71]
	v_mfma_f32_16x16x32_f16 v[64:67], v[184:187], v[160:163], v[64:67]
	v_mfma_f32_16x16x32_f16 v[144:147], v[180:183], v[132:135], v[144:147]
	v_mfma_f32_16x16x32_f16 v[120:123], v[184:187], v[120:123], v[140:143]
	v_mfma_f32_16x16x32_f16 v[116:119], v[180:183], v[148:151], v[116:119]
	v_mfma_f32_16x16x32_f16 v[112:115], v[188:191], v[148:151], v[112:115]
	v_mfma_f32_16x16x32_f16 v[92:95], v[180:183], v[156:159], v[92:95]
	v_mfma_f32_16x16x32_f16 v[84:87], v[188:191], v[156:159], v[84:87]
	v_mfma_f32_16x16x32_f16 v[68:71], v[180:183], v[172:175], v[68:71]
	v_mfma_f32_16x16x32_f16 v[64:67], v[188:191], v[172:175], v[64:67]
	v_mfma_f32_16x16x32_f16 v[120:123], v[188:191], v[132:135], v[120:123]
	s_mov_b32 m0, s15
	v_lshl_add_u64 v[200:201], s[20:21], 0, v[204:205]
	s_barrier
	ds_read_b128 v[132:135], v244 offset:16384
	ds_read_b128 v[136:139], v244 offset:17408
	ds_read_b128 v[140:143], v244 offset:18432
	ds_read_b128 v[148:151], v244 offset:19456
	ds_read_b128 v[152:155], v244 offset:20480
	ds_read_b128 v[156:159], v244 offset:21504
	ds_read_b128 v[160:163], v244 offset:22528
	ds_read_b128 v[172:175], v244 offset:23552
	global_load_lds_dwordx4 v[200:201], off
	v_lshl_add_u64 v[202:203], s[20:21], 0, v[208:209]
	s_mov_b32 m0, s25
	s_nop 0
	global_load_lds_dwordx4 v[202:203], off
	s_barrier
	s_waitcnt lgkmcnt(0)
	s_waitcnt lgkmcnt(0)
	v_mfma_f32_16x16x32_f16 v[60:63], v[80:83], v[132:135], v[60:63]
	v_mfma_f32_16x16x32_f16 v[56:59], v[96:99], v[132:135], v[56:59]
	v_mfma_f32_16x16x32_f16 v[44:47], v[80:83], v[140:143], v[44:47]
	v_mfma_f32_16x16x32_f16 v[40:43], v[96:99], v[140:143], v[40:43]
	v_mfma_f32_16x16x32_f16 v[28:31], v[80:83], v[152:155], v[28:31]
	v_mfma_f32_16x16x32_f16 v[24:27], v[96:99], v[152:155], v[24:27]
	v_mfma_f32_16x16x32_f16 v[12:15], v[80:83], v[160:163], v[12:15]
	v_mfma_f32_16x16x32_f16 v[8:11], v[96:99], v[160:163], v[8:11]
	v_mfma_f32_16x16x32_f16 v[60:63], v[88:91], v[136:139], v[60:63]
	v_mfma_f32_16x16x32_f16 v[56:59], v[100:103], v[136:139], v[56:59]
	v_mfma_f32_16x16x32_f16 v[44:47], v[88:91], v[148:151], v[44:47]
	v_mfma_f32_16x16x32_f16 v[40:43], v[100:103], v[148:151], v[40:43]
	v_mfma_f32_16x16x32_f16 v[28:31], v[88:91], v[156:159], v[28:31]
	v_mfma_f32_16x16x32_f16 v[24:27], v[100:103], v[156:159], v[24:27]
	v_mfma_f32_16x16x32_f16 v[12:15], v[88:91], v[172:175], v[12:15]
	v_mfma_f32_16x16x32_f16 v[8:11], v[100:103], v[172:175], v[8:11]
	s_barrier
	s_add_u32 s82, s18, 0x80000
	s_addc_u32 s83, s19, 0
	s_add_i32 s81, s76, s24
	v_lshl_add_u64 v[80:81], s[82:83], 0, v[206:207]
	s_mov_b32 m0, s81
	s_nop 0
	global_load_lds_dwordx4 v[80:81], off
	v_lshl_add_u64 v[80:81], s[82:83], 0, v[210:211]
	s_add_i32 m0, s81, 0x2000
	s_nop 0
	global_load_lds_dwordx4 v[80:81], off
	s_waitcnt vmcnt(6)
	s_barrier
	v_mfma_f32_16x16x32_f16 v[52:55], v[176:179], v[132:135], v[52:55]
	v_mfma_f32_16x16x32_f16 v[48:51], v[184:187], v[132:135], v[48:51]
	v_mfma_f32_16x16x32_f16 v[36:39], v[176:179], v[140:143], v[36:39]
	v_mfma_f32_16x16x32_f16 v[32:35], v[184:187], v[140:143], v[32:35]
	v_mfma_f32_16x16x32_f16 v[20:23], v[176:179], v[152:155], v[20:23]
	v_mfma_f32_16x16x32_f16 v[16:19], v[184:187], v[152:155], v[16:19]
	v_mfma_f32_16x16x32_f16 v[4:7], v[176:179], v[160:163], v[4:7]
	v_mfma_f32_16x16x32_f16 v[0:3], v[184:187], v[160:163], v[0:3]
	v_mfma_f32_16x16x32_f16 v[52:55], v[180:183], v[136:139], v[52:55]
	v_mfma_f32_16x16x32_f16 v[48:51], v[188:191], v[136:139], v[48:51]
	v_mfma_f32_16x16x32_f16 v[36:39], v[180:183], v[148:151], v[36:39]
	v_mfma_f32_16x16x32_f16 v[32:35], v[188:191], v[148:151], v[32:35]
	v_mfma_f32_16x16x32_f16 v[20:23], v[180:183], v[156:159], v[20:23]
	v_mfma_f32_16x16x32_f16 v[16:19], v[188:191], v[156:159], v[16:19]
	v_mfma_f32_16x16x32_f16 v[4:7], v[180:183], v[172:175], v[4:7]
	v_mfma_f32_16x16x32_f16 v[0:3], v[188:191], v[172:175], v[0:3]
	s_add_i32 s81, 0, 0x18000
	v_add_u32_e32 v100, s81, v241
	s_barrier
	ds_read_b128 v[80:83], v100
	ds_read_b128 v[88:91], v100 offset:1024
	ds_read_b128 v[96:99], v100 offset:2048
	ds_read_b128 v[100:103], v100 offset:3072
	s_add_u32 s20, s20, 0x80000
	s_addc_u32 s21, s21, 0
	s_mov_b32 m0, s26
	v_lshl_add_u64 v[140:141], s[20:21], 0, v[204:205]
	ds_read_b128 v[132:135], v244 offset:32768
	ds_read_b128 v[136:139], v244 offset:33792
	ds_read_b128 v[148:151], v244 offset:34816
	ds_read_b128 v[152:155], v244 offset:35840
	ds_read_b128 v[156:159], v244 offset:36864
	ds_read_b128 v[160:163], v244 offset:37888
	ds_read_b128 v[172:175], v244 offset:38912
	ds_read_b128 v[176:179], v244 offset:39936
	global_load_lds_dwordx4 v[140:141], off
	v_lshl_add_u64 v[140:141], s[20:21], 0, v[208:209]
	s_mov_b32 m0, s27
	s_nop 0
	global_load_lds_dwordx4 v[140:141], off
	s_waitcnt lgkmcnt(8)
	s_barrier
	s_waitcnt lgkmcnt(0)
	s_waitcnt lgkmcnt(0)
	v_mfma_f32_16x16x32_f16 v[140:143], v[80:83], v[132:135], v[168:171]
	v_mfma_f32_16x16x32_f16 v[168:171], v[88:91], v[136:139], v[140:143]
	v_mfma_f32_16x16x32_f16 v[140:143], v[96:99], v[132:135], v[164:167]
	v_mfma_f32_16x16x32_f16 v[128:131], v[80:83], v[148:151], v[128:131]
	v_mfma_f32_16x16x32_f16 v[124:127], v[96:99], v[148:151], v[124:127]
	v_mfma_f32_16x16x32_f16 v[108:111], v[80:83], v[156:159], v[108:111]
	v_mfma_f32_16x16x32_f16 v[104:107], v[96:99], v[156:159], v[104:107]
	v_mfma_f32_16x16x32_f16 v[76:79], v[80:83], v[172:175], v[76:79]
	v_mfma_f32_16x16x32_f16 v[72:75], v[96:99], v[172:175], v[72:75]
	v_mfma_f32_16x16x32_f16 v[164:167], v[100:103], v[136:139], v[140:143]
	v_mfma_f32_16x16x32_f16 v[128:131], v[88:91], v[152:155], v[128:131]
	v_mfma_f32_16x16x32_f16 v[124:127], v[100:103], v[152:155], v[124:127]
	v_mfma_f32_16x16x32_f16 v[108:111], v[88:91], v[160:163], v[108:111]
	v_mfma_f32_16x16x32_f16 v[104:107], v[100:103], v[160:163], v[104:107]
	v_mfma_f32_16x16x32_f16 v[76:79], v[88:91], v[176:179], v[76:79]
	v_mfma_f32_16x16x32_f16 v[72:75], v[100:103], v[176:179], v[72:75]
	s_barrier
	s_add_i32 s20, 0, 0x1c000
	v_add_u32_e32 v140, s20, v241
	s_add_i32 s21, s81, s24
	ds_read_b128 v[180:183], v140
	ds_read_b128 v[184:187], v140 offset:1024
	ds_read_b128 v[188:191], v140 offset:2048
	ds_read_b128 v[192:195], v140 offset:3072
	v_lshl_add_u64 v[140:141], v[196:197], 0, s[4:5]
	s_mov_b32 m0, s21
	s_nop 0
	global_load_lds_dwordx4 v[140:141], off
	v_lshl_add_u64 v[140:141], v[198:199], 0, s[4:5]
	s_add_i32 m0, s21, 0x2000
	s_nop 0
	global_load_lds_dwordx4 v[140:141], off
	s_barrier
	s_waitcnt lgkmcnt(0)
	s_waitcnt lgkmcnt(0)
	v_mfma_f32_16x16x32_f16 v[140:143], v[180:183], v[132:135], v[144:147]
	v_mfma_f32_16x16x32_f16 v[120:123], v[188:191], v[132:135], v[120:123]
	v_mfma_f32_16x16x32_f16 v[116:119], v[180:183], v[148:151], v[116:119]
	v_mfma_f32_16x16x32_f16 v[112:115], v[188:191], v[148:151], v[112:115]
	v_mfma_f32_16x16x32_f16 v[92:95], v[180:183], v[156:159], v[92:95]
	v_mfma_f32_16x16x32_f16 v[84:87], v[188:191], v[156:159], v[84:87]
	v_mfma_f32_16x16x32_f16 v[68:71], v[180:183], v[172:175], v[68:71]
	v_mfma_f32_16x16x32_f16 v[64:67], v[188:191], v[172:175], v[64:67]
	v_mfma_f32_16x16x32_f16 v[144:147], v[184:187], v[136:139], v[140:143]
	v_mfma_f32_16x16x32_f16 v[140:143], v[192:195], v[136:139], v[120:123]
	v_mfma_f32_16x16x32_f16 v[116:119], v[184:187], v[152:155], v[116:119]
	v_mfma_f32_16x16x32_f16 v[112:115], v[192:195], v[152:155], v[112:115]
	v_mfma_f32_16x16x32_f16 v[92:95], v[184:187], v[160:163], v[92:95]
	v_mfma_f32_16x16x32_f16 v[84:87], v[192:195], v[160:163], v[84:87]
	v_mfma_f32_16x16x32_f16 v[68:71], v[184:187], v[176:179], v[68:71]
	v_mfma_f32_16x16x32_f16 v[64:67], v[192:195], v[176:179], v[64:67]
	s_mov_b32 m0, s35
	v_lshl_add_u64 v[176:177], v[200:201], 0, s[4:5]
	s_barrier
	ds_read_b128 v[120:123], v244 offset:49152
	ds_read_b128 v[132:135], v244 offset:50176
	ds_read_b128 v[136:139], v244 offset:51200
	ds_read_b128 v[148:151], v244 offset:52224
	ds_read_b128 v[152:155], v244 offset:53248
	ds_read_b128 v[156:159], v244 offset:54272
	ds_read_b128 v[160:163], v244 offset:55296
	ds_read_b128 v[172:175], v244 offset:56320
	global_load_lds_dwordx4 v[176:177], off
	v_lshl_add_u64 v[176:177], v[202:203], 0, s[4:5]
	s_mov_b32 m0, s68
	s_nop 0
	global_load_lds_dwordx4 v[176:177], off
	s_barrier
	s_waitcnt lgkmcnt(0)
	s_waitcnt lgkmcnt(0)
	v_mfma_f32_16x16x32_f16 v[60:63], v[80:83], v[120:123], v[60:63]
	v_mfma_f32_16x16x32_f16 v[56:59], v[96:99], v[120:123], v[56:59]
	v_mfma_f32_16x16x32_f16 v[44:47], v[80:83], v[136:139], v[44:47]
	v_mfma_f32_16x16x32_f16 v[40:43], v[96:99], v[136:139], v[40:43]
	v_mfma_f32_16x16x32_f16 v[28:31], v[80:83], v[152:155], v[28:31]
	v_mfma_f32_16x16x32_f16 v[24:27], v[96:99], v[152:155], v[24:27]
	v_mfma_f32_16x16x32_f16 v[12:15], v[80:83], v[160:163], v[12:15]
	v_mfma_f32_16x16x32_f16 v[8:11], v[96:99], v[160:163], v[8:11]
	v_mfma_f32_16x16x32_f16 v[60:63], v[88:91], v[132:135], v[60:63]
	v_mfma_f32_16x16x32_f16 v[56:59], v[100:103], v[132:135], v[56:59]
	v_mfma_f32_16x16x32_f16 v[44:47], v[88:91], v[148:151], v[44:47]
	v_mfma_f32_16x16x32_f16 v[40:43], v[100:103], v[148:151], v[40:43]
	v_mfma_f32_16x16x32_f16 v[28:31], v[88:91], v[156:159], v[28:31]
	v_mfma_f32_16x16x32_f16 v[24:27], v[100:103], v[156:159], v[24:27]
	v_mfma_f32_16x16x32_f16 v[12:15], v[88:91], v[172:175], v[12:15]
	v_mfma_f32_16x16x32_f16 v[8:11], v[100:103], v[172:175], v[8:11]
	s_barrier
	s_add_u32 s18, s18, 0x80080
	s_addc_u32 s19, s19, 0
	s_add_i32 s20, s20, s24
	v_lshl_add_u64 v[80:81], s[18:19], 0, v[206:207]
	s_mov_b32 m0, s20
	s_nop 0
	global_load_lds_dwordx4 v[80:81], off
	v_lshl_add_u64 v[80:81], s[18:19], 0, v[210:211]
	s_add_i32 m0, s20, 0x2000
	s_nop 0
	global_load_lds_dwordx4 v[80:81], off
	s_waitcnt vmcnt(6)
	s_barrier
	v_mfma_f32_16x16x32_f16 v[52:55], v[180:183], v[120:123], v[52:55]
	v_mfma_f32_16x16x32_f16 v[48:51], v[188:191], v[120:123], v[48:51]
	v_mfma_f32_16x16x32_f16 v[36:39], v[180:183], v[136:139], v[36:39]
	v_mfma_f32_16x16x32_f16 v[32:35], v[188:191], v[136:139], v[32:35]
	v_mfma_f32_16x16x32_f16 v[20:23], v[180:183], v[152:155], v[20:23]
	v_mfma_f32_16x16x32_f16 v[16:19], v[188:191], v[152:155], v[16:19]
	v_mfma_f32_16x16x32_f16 v[4:7], v[180:183], v[160:163], v[4:7]
	v_mfma_f32_16x16x32_f16 v[0:3], v[188:191], v[160:163], v[0:3]
	v_mfma_f32_16x16x32_f16 v[52:55], v[184:187], v[132:135], v[52:55]
	v_mfma_f32_16x16x32_f16 v[48:51], v[192:195], v[132:135], v[48:51]
	v_mfma_f32_16x16x32_f16 v[36:39], v[184:187], v[148:151], v[36:39]
	v_mfma_f32_16x16x32_f16 v[32:35], v[192:195], v[148:151], v[32:35]
	v_mfma_f32_16x16x32_f16 v[20:23], v[184:187], v[156:159], v[20:23]
	v_mfma_f32_16x16x32_f16 v[16:19], v[192:195], v[156:159], v[16:19]
	v_mfma_f32_16x16x32_f16 v[4:7], v[184:187], v[172:175], v[4:7]
	v_mfma_f32_16x16x32_f16 v[0:3], v[192:195], v[172:175], v[0:3]
	s_add_i32 s80, s80, 2
	s_add_u32 s16, s16, 0x100
	s_addc_u32 s17, s17, 0
	s_add_u32 s78, s78, 0x100
	s_addc_u32 s79, s79, 0
	s_cmp_gt_u32 s80, 29
	s_barrier
	s_cbranch_scc0 .LBB0_647
	s_setprio 0
	s_lshl_b32 s7, s14, 8
	s_add_i32 s9, s7, 0xffffe000
	s_lshr_b32 s9, s9, 11
	s_mulk_i32 s9, 0x1800
	s_addk_i32 s9, 0x1800
	s_cmp_gt_i32 s14, 31
	s_cselect_b32 s16, s9, 0
	s_ashr_i32 s17, s16, 31
	v_lshl_or_b32 v120, s30, 8, v242
	s_lshl_b64 s[16:17], s[16:17], 2
	s_add_u32 s16, s29, s16
	v_ashrrev_i32_e32 v121, 31, v120
	v_add_u32_e32 v122, s7, v240
	s_addc_u32 s17, s34, s17
	v_lshlrev_b64 v[220:221], 1, v[120:121]
	v_ashrrev_i32_e32 v123, 31, v122
	v_lshl_add_u64 v[88:89], v[120:121], 2, s[16:17]
	v_lshl_add_u64 v[120:121], s[40:41], 0, v[220:221]
	v_lshlrev_b64 v[236:237], 12, v[122:123]
	v_lshl_add_u64 v[132:133], v[120:121], 0, v[236:237]
	global_load_dwordx4 v[96:99], v[88:89], off offset:16
	global_load_dwordx4 v[100:103], v[88:89], off
	global_load_dwordx4 v[80:83], v[88:89], off offset:528
	s_nop 0
	global_load_dwordx4 v[88:91], v[88:89], off offset:512
	s_nop 0
	global_load_dwordx4 v[246:249], v[132:133], off nt
	global_load_dwordx4 v[200:203], v[132:133], off offset:256 nt
	v_or_b32_e32 v132, 16, v122
	v_ashrrev_i32_e32 v133, 31, v132
	v_lshlrev_b64 v[234:235], 12, v[132:133]
	v_lshl_add_u64 v[132:133], v[120:121], 0, v[234:235]
	global_load_dwordx4 v[196:199], v[132:133], off nt
	global_load_dwordx4 v[192:195], v[132:133], off offset:256 nt
	v_or_b32_e32 v132, 32, v122
	v_ashrrev_i32_e32 v133, 31, v132
	v_lshlrev_b64 v[232:233], 12, v[132:133]
	v_lshl_add_u64 v[132:133], v[120:121], 0, v[232:233]
	global_load_dwordx4 v[188:191], v[132:133], off nt
	global_load_dwordx4 v[184:187], v[132:133], off offset:256 nt
	v_or_b32_e32 v122, 48, v122
	v_ashrrev_i32_e32 v123, 31, v122
	v_lshlrev_b64 v[230:231], 12, v[122:123]
	v_lshl_add_u64 v[122:123], v[120:121], 0, v[230:231]
	global_load_dwordx4 v[180:183], v[122:123], off nt
	global_load_dwordx4 v[176:179], v[122:123], off offset:256 nt
	s_mov_b64 s[16:17], 0x80000
	v_lshl_add_u64 v[228:229], v[236:237], 0, s[16:17]
	v_lshl_add_u64 v[122:123], v[120:121], 0, v[228:229]
	global_load_dwordx4 v[172:175], v[122:123], off nt
	global_load_dwordx4 v[160:163], v[122:123], off offset:256 nt
	s_mov_b64 s[16:17], 0x90000
	v_lshl_add_u64 v[226:227], v[236:237], 0, s[16:17]
	v_lshl_add_u64 v[122:123], v[120:121], 0, v[226:227]
	global_load_dwordx4 v[156:159], v[122:123], off nt
	global_load_dwordx4 v[152:155], v[122:123], off offset:256 nt
	s_mov_b64 s[16:17], 0xa0000
	v_lshl_add_u64 v[224:225], v[236:237], 0, s[16:17]
	v_lshl_add_u64 v[122:123], v[120:121], 0, v[224:225]
	global_load_dwordx4 v[148:151], v[122:123], off nt
	global_load_dwordx4 v[136:139], v[122:123], off offset:256 nt
	s_mov_b64 s[16:17], 0xb0000
	v_lshl_add_u64 v[222:223], v[236:237], 0, s[16:17]
	v_lshl_add_u64 v[120:121], v[120:121], 0, v[222:223]
	global_load_dwordx4 v[132:135], v[120:121], off nt
	s_nop 0
	global_load_dwordx4 v[120:123], v[120:121], off offset:256 nt
	s_and_b64 vcc, exec, s[2:3]
	s_mov_b32 s30, s6
	s_mov_b32 s14, s8
	s_mov_b64 s[18:19], s[12:13]
	s_mov_b64 s[16:17], s[10:11]
	s_waitcnt vmcnt(0)
	v_cvt_f32_f16_e32 v250, v246
	v_cvt_f32_f16_sdwa v251, v246 dst_sel:DWORD dst_unused:UNUSED_PAD src0_sel:WORD_1
	v_pk_fma_f32 v[168:169], v[168:169], v[100:101], v[250:251]
	s_nop 0
	v_cvt_pk_f16_f32 v246, v168, v169
	v_cvt_f32_f16_e32 v168, v248
	v_cvt_f32_f16_sdwa v169, v248 dst_sel:DWORD dst_unused:UNUSED_PAD src0_sel:WORD_1
	v_pk_fma_f32 v[164:165], v[164:165], v[96:97], v[168:169]
	s_nop 0
	v_cvt_pk_f16_f32 v248, v164, v165
	v_cvt_f32_f16_e32 v164, v247
	v_cvt_f32_f16_sdwa v165, v247 dst_sel:DWORD dst_unused:UNUSED_PAD src0_sel:WORD_1
	v_pk_fma_f32 v[164:165], v[170:171], v[102:103], v[164:165]
	s_nop 0
	v_cvt_pk_f16_f32 v247, v164, v165
	v_cvt_f32_f16_e32 v164, v249
	v_cvt_f32_f16_sdwa v165, v249 dst_sel:DWORD dst_unused:UNUSED_PAD src0_sel:WORD_1
	v_pk_fma_f32 v[164:165], v[166:167], v[98:99], v[164:165]
	s_nop 0
	v_cvt_pk_f16_f32 v249, v164, v165
	v_lshl_add_u64 v[164:165], s[0:1], 0, v[236:237]
	v_lshl_add_u64 v[168:169], v[164:165], 0, v[220:221]
	v_cvt_f32_f16_e32 v164, v200
	v_cvt_f32_f16_sdwa v165, v200 dst_sel:DWORD dst_unused:UNUSED_PAD src0_sel:WORD_1
	global_store_dwordx4 v[168:169], v[246:249], off
	v_pk_fma_f32 v[144:145], v[144:145], v[88:89], v[164:165]
	s_nop 0
	v_cvt_pk_f16_f32 v164, v144, v145
	v_cvt_f32_f16_e32 v144, v202
	v_cvt_f32_f16_sdwa v145, v202 dst_sel:DWORD dst_unused:UNUSED_PAD src0_sel:WORD_1
	v_pk_fma_f32 v[140:141], v[140:141], v[80:81], v[144:145]
	s_nop 0
	v_cvt_pk_f16_f32 v166, v140, v141
	v_cvt_f32_f16_e32 v140, v201
	v_cvt_f32_f16_sdwa v141, v201 dst_sel:DWORD dst_unused:UNUSED_PAD src0_sel:WORD_1
	v_pk_fma_f32 v[140:141], v[146:147], v[90:91], v[140:141]
	s_nop 0
	v_cvt_pk_f16_f32 v165, v140, v141
	v_cvt_f32_f16_e32 v140, v203
	v_cvt_f32_f16_sdwa v141, v203 dst_sel:DWORD dst_unused:UNUSED_PAD src0_sel:WORD_1
	v_pk_fma_f32 v[140:141], v[142:143], v[82:83], v[140:141]
	s_nop 0
	v_cvt_pk_f16_f32 v167, v140, v141
	v_cvt_f32_f16_e32 v140, v196
	v_cvt_f32_f16_sdwa v141, v196 dst_sel:DWORD dst_unused:UNUSED_PAD src0_sel:WORD_1
	global_store_dwordx4 v[168:169], v[164:167], off offset:256
	v_pk_fma_f32 v[128:129], v[128:129], v[100:101], v[140:141]
	s_nop 0
	v_cvt_pk_f16_f32 v140, v128, v129
	v_cvt_f32_f16_e32 v128, v198
	v_cvt_f32_f16_sdwa v129, v198 dst_sel:DWORD dst_unused:UNUSED_PAD src0_sel:WORD_1
	v_pk_fma_f32 v[124:125], v[124:125], v[96:97], v[128:129]
	s_nop 0
	v_cvt_pk_f16_f32 v142, v124, v125
	v_cvt_f32_f16_e32 v124, v197
	v_cvt_f32_f16_sdwa v125, v197 dst_sel:DWORD dst_unused:UNUSED_PAD src0_sel:WORD_1
	v_pk_fma_f32 v[124:125], v[130:131], v[102:103], v[124:125]
	s_nop 0
	v_cvt_pk_f16_f32 v141, v124, v125
	v_cvt_f32_f16_e32 v124, v199
	v_cvt_f32_f16_sdwa v125, v199 dst_sel:DWORD dst_unused:UNUSED_PAD src0_sel:WORD_1
	v_pk_fma_f32 v[124:125], v[126:127], v[98:99], v[124:125]
	s_nop 0
	v_cvt_pk_f16_f32 v143, v124, v125
	v_lshl_add_u64 v[124:125], s[0:1], 0, v[234:235]
	v_lshl_add_u64 v[128:129], v[124:125], 0, v[220:221]
	v_cvt_f32_f16_e32 v124, v192
	v_cvt_f32_f16_sdwa v125, v192 dst_sel:DWORD dst_unused:UNUSED_PAD src0_sel:WORD_1
	global_store_dwordx4 v[128:129], v[140:143], off
	v_pk_fma_f32 v[116:117], v[116:117], v[88:89], v[124:125]
	s_nop 0
	v_cvt_pk_f16_f32 v124, v116, v117
	v_cvt_f32_f16_e32 v116, v194
	v_cvt_f32_f16_sdwa v117, v194 dst_sel:DWORD dst_unused:UNUSED_PAD src0_sel:WORD_1
	v_pk_fma_f32 v[112:113], v[112:113], v[80:81], v[116:117]
	s_nop 0
	v_cvt_pk_f16_f32 v126, v112, v113
	v_cvt_f32_f16_e32 v112, v193
	v_cvt_f32_f16_sdwa v113, v193 dst_sel:DWORD dst_unused:UNUSED_PAD src0_sel:WORD_1
	v_pk_fma_f32 v[112:113], v[118:119], v[90:91], v[112:113]
	s_nop 0
	v_cvt_pk_f16_f32 v125, v112, v113
	v_cvt_f32_f16_e32 v112, v195
	v_cvt_f32_f16_sdwa v113, v195 dst_sel:DWORD dst_unused:UNUSED_PAD src0_sel:WORD_1
	v_pk_fma_f32 v[112:113], v[114:115], v[82:83], v[112:113]
	s_nop 0
	v_cvt_pk_f16_f32 v127, v112, v113
	v_cvt_f32_f16_e32 v112, v188
	v_cvt_f32_f16_sdwa v113, v188 dst_sel:DWORD dst_unused:UNUSED_PAD src0_sel:WORD_1
	global_store_dwordx4 v[128:129], v[124:127], off offset:256
	v_pk_fma_f32 v[108:109], v[108:109], v[100:101], v[112:113]
	s_nop 0
	v_cvt_pk_f16_f32 v112, v108, v109
	v_cvt_f32_f16_e32 v108, v190
	v_cvt_f32_f16_sdwa v109, v190 dst_sel:DWORD dst_unused:UNUSED_PAD src0_sel:WORD_1
	v_pk_fma_f32 v[104:105], v[104:105], v[96:97], v[108:109]
	s_nop 0
	v_cvt_pk_f16_f32 v114, v104, v105
	v_cvt_f32_f16_e32 v104, v189
	v_cvt_f32_f16_sdwa v105, v189 dst_sel:DWORD dst_unused:UNUSED_PAD src0_sel:WORD_1
	v_pk_fma_f32 v[104:105], v[110:111], v[102:103], v[104:105]
	s_nop 0
	v_cvt_pk_f16_f32 v113, v104, v105
	v_cvt_f32_f16_e32 v104, v191
	v_cvt_f32_f16_sdwa v105, v191 dst_sel:DWORD dst_unused:UNUSED_PAD src0_sel:WORD_1
	v_pk_fma_f32 v[104:105], v[106:107], v[98:99], v[104:105]
	s_nop 0
	v_cvt_pk_f16_f32 v115, v104, v105
	v_lshl_add_u64 v[104:105], s[0:1], 0, v[232:233]
	v_lshl_add_u64 v[108:109], v[104:105], 0, v[220:221]
	v_cvt_f32_f16_e32 v104, v184
	v_cvt_f32_f16_sdwa v105, v184 dst_sel:DWORD dst_unused:UNUSED_PAD src0_sel:WORD_1
	global_store_dwordx4 v[108:109], v[112:115], off
	v_pk_fma_f32 v[92:93], v[92:93], v[88:89], v[104:105]
	s_nop 0
	v_cvt_pk_f16_f32 v104, v92, v93
	v_cvt_f32_f16_e32 v92, v186
	v_cvt_f32_f16_sdwa v93, v186 dst_sel:DWORD dst_unused:UNUSED_PAD src0_sel:WORD_1
	v_pk_fma_f32 v[84:85], v[84:85], v[80:81], v[92:93]
	s_nop 0
	v_cvt_pk_f16_f32 v106, v84, v85
	v_cvt_f32_f16_e32 v84, v185
	v_cvt_f32_f16_sdwa v85, v185 dst_sel:DWORD dst_unused:UNUSED_PAD src0_sel:WORD_1
	v_pk_fma_f32 v[84:85], v[94:95], v[90:91], v[84:85]
	s_nop 0
	v_cvt_pk_f16_f32 v105, v84, v85
	v_cvt_f32_f16_e32 v84, v187
	v_cvt_f32_f16_sdwa v85, v187 dst_sel:DWORD dst_unused:UNUSED_PAD src0_sel:WORD_1
	v_pk_fma_f32 v[84:85], v[86:87], v[82:83], v[84:85]
	s_nop 0
	v_cvt_pk_f16_f32 v107, v84, v85
	v_cvt_f32_f16_e32 v84, v180
	v_cvt_f32_f16_sdwa v85, v180 dst_sel:DWORD dst_unused:UNUSED_PAD src0_sel:WORD_1
	global_store_dwordx4 v[108:109], v[104:107], off offset:256
	v_pk_fma_f32 v[76:77], v[76:77], v[100:101], v[84:85]
	s_nop 0
	v_cvt_pk_f16_f32 v84, v76, v77
	v_cvt_f32_f16_e32 v76, v182
	v_cvt_f32_f16_sdwa v77, v182 dst_sel:DWORD dst_unused:UNUSED_PAD src0_sel:WORD_1
	v_pk_fma_f32 v[72:73], v[72:73], v[96:97], v[76:77]
	s_nop 0
	v_cvt_pk_f16_f32 v86, v72, v73
	v_cvt_f32_f16_e32 v72, v181
	v_cvt_f32_f16_sdwa v73, v181 dst_sel:DWORD dst_unused:UNUSED_PAD src0_sel:WORD_1
	v_pk_fma_f32 v[72:73], v[78:79], v[102:103], v[72:73]
	s_nop 0
	v_cvt_pk_f16_f32 v85, v72, v73
	v_cvt_f32_f16_e32 v72, v183
	v_cvt_f32_f16_sdwa v73, v183 dst_sel:DWORD dst_unused:UNUSED_PAD src0_sel:WORD_1
	v_pk_fma_f32 v[72:73], v[74:75], v[98:99], v[72:73]
	s_nop 0
	v_cvt_pk_f16_f32 v87, v72, v73
	v_lshl_add_u64 v[72:73], s[0:1], 0, v[230:231]
	v_lshl_add_u64 v[76:77], v[72:73], 0, v[220:221]
	v_cvt_f32_f16_e32 v72, v176
	v_cvt_f32_f16_sdwa v73, v176 dst_sel:DWORD dst_unused:UNUSED_PAD src0_sel:WORD_1
	global_store_dwordx4 v[76:77], v[84:87], off
	v_pk_fma_f32 v[68:69], v[68:69], v[88:89], v[72:73]
	s_nop 0
	v_cvt_pk_f16_f32 v72, v68, v69
	v_cvt_f32_f16_e32 v68, v178
	v_cvt_f32_f16_sdwa v69, v178 dst_sel:DWORD dst_unused:UNUSED_PAD src0_sel:WORD_1
	v_pk_fma_f32 v[64:65], v[64:65], v[80:81], v[68:69]
	s_nop 0
	v_cvt_pk_f16_f32 v74, v64, v65
	v_cvt_f32_f16_e32 v64, v177
	v_cvt_f32_f16_sdwa v65, v177 dst_sel:DWORD dst_unused:UNUSED_PAD src0_sel:WORD_1
	v_pk_fma_f32 v[64:65], v[70:71], v[90:91], v[64:65]
	s_nop 0
	v_cvt_pk_f16_f32 v73, v64, v65
	v_cvt_f32_f16_e32 v64, v179
	v_cvt_f32_f16_sdwa v65, v179 dst_sel:DWORD dst_unused:UNUSED_PAD src0_sel:WORD_1
	v_pk_fma_f32 v[64:65], v[66:67], v[82:83], v[64:65]
	s_nop 0
	v_cvt_pk_f16_f32 v75, v64, v65
	v_cvt_f32_f16_e32 v64, v172
	v_cvt_f32_f16_sdwa v65, v172 dst_sel:DWORD dst_unused:UNUSED_PAD src0_sel:WORD_1
	global_store_dwordx4 v[76:77], v[72:75], off offset:256
	v_pk_fma_f32 v[60:61], v[60:61], v[100:101], v[64:65]
	s_nop 0
	v_cvt_pk_f16_f32 v64, v60, v61
	v_cvt_f32_f16_e32 v60, v174
	v_cvt_f32_f16_sdwa v61, v174 dst_sel:DWORD dst_unused:UNUSED_PAD src0_sel:WORD_1
	v_pk_fma_f32 v[56:57], v[56:57], v[96:97], v[60:61]
	s_nop 0
	v_cvt_pk_f16_f32 v66, v56, v57
	v_cvt_f32_f16_e32 v56, v173
	v_cvt_f32_f16_sdwa v57, v173 dst_sel:DWORD dst_unused:UNUSED_PAD src0_sel:WORD_1
	v_pk_fma_f32 v[56:57], v[62:63], v[102:103], v[56:57]
	s_nop 0
	v_cvt_pk_f16_f32 v65, v56, v57
	v_cvt_f32_f16_e32 v56, v175
	v_cvt_f32_f16_sdwa v57, v175 dst_sel:DWORD dst_unused:UNUSED_PAD src0_sel:WORD_1
	v_pk_fma_f32 v[56:57], v[58:59], v[98:99], v[56:57]
	s_nop 0
	v_cvt_pk_f16_f32 v67, v56, v57
	v_lshl_add_u64 v[56:57], s[0:1], 0, v[228:229]
	v_lshl_add_u64 v[60:61], v[56:57], 0, v[220:221]
	v_cvt_f32_f16_e32 v56, v160
	v_cvt_f32_f16_sdwa v57, v160 dst_sel:DWORD dst_unused:UNUSED_PAD src0_sel:WORD_1
	global_store_dwordx4 v[60:61], v[64:67], off
	v_pk_fma_f32 v[52:53], v[52:53], v[88:89], v[56:57]
	s_nop 0
	v_cvt_pk_f16_f32 v56, v52, v53
	v_cvt_f32_f16_e32 v52, v162
	v_cvt_f32_f16_sdwa v53, v162 dst_sel:DWORD dst_unused:UNUSED_PAD src0_sel:WORD_1
	v_pk_fma_f32 v[48:49], v[48:49], v[80:81], v[52:53]
	s_nop 0
	v_cvt_pk_f16_f32 v58, v48, v49
	v_cvt_f32_f16_e32 v48, v161
	v_cvt_f32_f16_sdwa v49, v161 dst_sel:DWORD dst_unused:UNUSED_PAD src0_sel:WORD_1
	v_pk_fma_f32 v[48:49], v[54:55], v[90:91], v[48:49]
	s_nop 0
	v_cvt_pk_f16_f32 v57, v48, v49
	v_cvt_f32_f16_e32 v48, v163
	v_cvt_f32_f16_sdwa v49, v163 dst_sel:DWORD dst_unused:UNUSED_PAD src0_sel:WORD_1
	v_pk_fma_f32 v[48:49], v[50:51], v[82:83], v[48:49]
	s_nop 0
	v_cvt_pk_f16_f32 v59, v48, v49
	v_cvt_f32_f16_e32 v48, v156
	v_cvt_f32_f16_sdwa v49, v156 dst_sel:DWORD dst_unused:UNUSED_PAD src0_sel:WORD_1
	global_store_dwordx4 v[60:61], v[56:59], off offset:256
	v_pk_fma_f32 v[44:45], v[44:45], v[100:101], v[48:49]
	s_nop 0
	v_cvt_pk_f16_f32 v48, v44, v45
	v_cvt_f32_f16_e32 v44, v158
	v_cvt_f32_f16_sdwa v45, v158 dst_sel:DWORD dst_unused:UNUSED_PAD src0_sel:WORD_1
	v_pk_fma_f32 v[40:41], v[40:41], v[96:97], v[44:45]
	s_nop 0
	v_cvt_pk_f16_f32 v50, v40, v41
	v_cvt_f32_f16_e32 v40, v157
	v_cvt_f32_f16_sdwa v41, v157 dst_sel:DWORD dst_unused:UNUSED_PAD src0_sel:WORD_1
	v_pk_fma_f32 v[40:41], v[46:47], v[102:103], v[40:41]
	s_nop 0
	v_cvt_pk_f16_f32 v49, v40, v41
	v_cvt_f32_f16_e32 v40, v159
	v_cvt_f32_f16_sdwa v41, v159 dst_sel:DWORD dst_unused:UNUSED_PAD src0_sel:WORD_1
	v_pk_fma_f32 v[40:41], v[42:43], v[98:99], v[40:41]
	s_nop 0
	v_cvt_pk_f16_f32 v51, v40, v41
	v_lshl_add_u64 v[40:41], s[0:1], 0, v[226:227]
	v_lshl_add_u64 v[44:45], v[40:41], 0, v[220:221]
	v_cvt_f32_f16_e32 v40, v152
	v_cvt_f32_f16_sdwa v41, v152 dst_sel:DWORD dst_unused:UNUSED_PAD src0_sel:WORD_1
	global_store_dwordx4 v[44:45], v[48:51], off
	v_pk_fma_f32 v[36:37], v[36:37], v[88:89], v[40:41]
	s_nop 0
	v_cvt_pk_f16_f32 v40, v36, v37
	v_cvt_f32_f16_e32 v36, v154
	v_cvt_f32_f16_sdwa v37, v154 dst_sel:DWORD dst_unused:UNUSED_PAD src0_sel:WORD_1
	v_pk_fma_f32 v[32:33], v[32:33], v[80:81], v[36:37]
	s_nop 0
	v_cvt_pk_f16_f32 v42, v32, v33
	v_cvt_f32_f16_e32 v32, v153
	v_cvt_f32_f16_sdwa v33, v153 dst_sel:DWORD dst_unused:UNUSED_PAD src0_sel:WORD_1
	v_pk_fma_f32 v[32:33], v[38:39], v[90:91], v[32:33]
	s_nop 0
	v_cvt_pk_f16_f32 v41, v32, v33
	v_cvt_f32_f16_e32 v32, v155
	v_cvt_f32_f16_sdwa v33, v155 dst_sel:DWORD dst_unused:UNUSED_PAD src0_sel:WORD_1
	v_pk_fma_f32 v[32:33], v[34:35], v[82:83], v[32:33]
	s_nop 0
	v_cvt_pk_f16_f32 v43, v32, v33
	v_cvt_f32_f16_e32 v32, v148
	v_cvt_f32_f16_sdwa v33, v148 dst_sel:DWORD dst_unused:UNUSED_PAD src0_sel:WORD_1
	global_store_dwordx4 v[44:45], v[40:43], off offset:256
	v_pk_fma_f32 v[28:29], v[28:29], v[100:101], v[32:33]
	s_nop 0
	v_cvt_pk_f16_f32 v32, v28, v29
	v_cvt_f32_f16_e32 v28, v150
	v_cvt_f32_f16_sdwa v29, v150 dst_sel:DWORD dst_unused:UNUSED_PAD src0_sel:WORD_1
	v_pk_fma_f32 v[24:25], v[24:25], v[96:97], v[28:29]
	s_nop 0
	v_cvt_pk_f16_f32 v34, v24, v25
	v_cvt_f32_f16_e32 v24, v149
	v_cvt_f32_f16_sdwa v25, v149 dst_sel:DWORD dst_unused:UNUSED_PAD src0_sel:WORD_1
	v_pk_fma_f32 v[24:25], v[30:31], v[102:103], v[24:25]
	s_nop 0
	v_cvt_pk_f16_f32 v33, v24, v25
	v_cvt_f32_f16_e32 v24, v151
	v_cvt_f32_f16_sdwa v25, v151 dst_sel:DWORD dst_unused:UNUSED_PAD src0_sel:WORD_1
	v_pk_fma_f32 v[24:25], v[26:27], v[98:99], v[24:25]
	s_nop 0
	v_cvt_pk_f16_f32 v35, v24, v25
	v_lshl_add_u64 v[24:25], s[0:1], 0, v[224:225]
	v_lshl_add_u64 v[28:29], v[24:25], 0, v[220:221]
	v_cvt_f32_f16_e32 v24, v136
	v_cvt_f32_f16_sdwa v25, v136 dst_sel:DWORD dst_unused:UNUSED_PAD src0_sel:WORD_1
	global_store_dwordx4 v[28:29], v[32:35], off
	v_pk_fma_f32 v[20:21], v[20:21], v[88:89], v[24:25]
	s_nop 0
	v_cvt_pk_f16_f32 v24, v20, v21
	v_cvt_f32_f16_e32 v20, v138
	v_cvt_f32_f16_sdwa v21, v138 dst_sel:DWORD dst_unused:UNUSED_PAD src0_sel:WORD_1
	v_pk_fma_f32 v[16:17], v[16:17], v[80:81], v[20:21]
	s_nop 0
	v_cvt_pk_f16_f32 v26, v16, v17
	v_cvt_f32_f16_e32 v16, v137
	v_cvt_f32_f16_sdwa v17, v137 dst_sel:DWORD dst_unused:UNUSED_PAD src0_sel:WORD_1
	v_pk_fma_f32 v[16:17], v[22:23], v[90:91], v[16:17]
	s_nop 0
	v_cvt_pk_f16_f32 v25, v16, v17
	v_cvt_f32_f16_e32 v16, v139
	v_cvt_f32_f16_sdwa v17, v139 dst_sel:DWORD dst_unused:UNUSED_PAD src0_sel:WORD_1
	v_pk_fma_f32 v[16:17], v[18:19], v[82:83], v[16:17]
	s_nop 0
	v_cvt_pk_f16_f32 v27, v16, v17
	v_cvt_f32_f16_e32 v16, v132
	v_cvt_f32_f16_sdwa v17, v132 dst_sel:DWORD dst_unused:UNUSED_PAD src0_sel:WORD_1
	global_store_dwordx4 v[28:29], v[24:27], off offset:256
	v_pk_fma_f32 v[12:13], v[12:13], v[100:101], v[16:17]
	s_nop 0
	v_cvt_pk_f16_f32 v16, v12, v13
	v_cvt_f32_f16_e32 v12, v134
	v_cvt_f32_f16_sdwa v13, v134 dst_sel:DWORD dst_unused:UNUSED_PAD src0_sel:WORD_1
	v_pk_fma_f32 v[8:9], v[8:9], v[96:97], v[12:13]
	s_nop 0
	v_cvt_pk_f16_f32 v18, v8, v9
	v_cvt_f32_f16_e32 v8, v133
	v_cvt_f32_f16_sdwa v9, v133 dst_sel:DWORD dst_unused:UNUSED_PAD src0_sel:WORD_1
	v_pk_fma_f32 v[8:9], v[14:15], v[102:103], v[8:9]
	s_nop 0
	v_cvt_pk_f16_f32 v17, v8, v9
	v_cvt_f32_f16_e32 v8, v135
	v_cvt_f32_f16_sdwa v9, v135 dst_sel:DWORD dst_unused:UNUSED_PAD src0_sel:WORD_1
	v_pk_fma_f32 v[8:9], v[10:11], v[98:99], v[8:9]
	s_nop 0
	v_cvt_pk_f16_f32 v19, v8, v9
	v_lshl_add_u64 v[8:9], s[0:1], 0, v[222:223]
	v_lshl_add_u64 v[12:13], v[8:9], 0, v[220:221]
	v_cvt_f32_f16_e32 v8, v120
	v_cvt_f32_f16_sdwa v9, v120 dst_sel:DWORD dst_unused:UNUSED_PAD src0_sel:WORD_1
	global_store_dwordx4 v[12:13], v[16:19], off
	v_pk_fma_f32 v[4:5], v[4:5], v[88:89], v[8:9]
	s_nop 0
	v_cvt_pk_f16_f32 v8, v4, v5
	v_cvt_f32_f16_e32 v4, v122
	v_cvt_f32_f16_sdwa v5, v122 dst_sel:DWORD dst_unused:UNUSED_PAD src0_sel:WORD_1
	v_pk_fma_f32 v[0:1], v[0:1], v[80:81], v[4:5]
	s_nop 0
	v_cvt_pk_f16_f32 v10, v0, v1
	v_cvt_f32_f16_e32 v0, v121
	v_cvt_f32_f16_sdwa v1, v121 dst_sel:DWORD dst_unused:UNUSED_PAD src0_sel:WORD_1
	v_pk_fma_f32 v[0:1], v[6:7], v[90:91], v[0:1]
	s_nop 0
	v_cvt_pk_f16_f32 v9, v0, v1
	v_cvt_f32_f16_e32 v0, v123
	v_cvt_f32_f16_sdwa v1, v123 dst_sel:DWORD dst_unused:UNUSED_PAD src0_sel:WORD_1
	v_pk_fma_f32 v[0:1], v[2:3], v[82:83], v[0:1]
	s_nop 0
	v_cvt_pk_f16_f32 v11, v0, v1
	global_store_dwordx4 v[12:13], v[8:11], off offset:256
	s_cbranch_vccz .LBB0_640
	s_waitcnt vmcnt(0)
	s_cmpk_gt_u32 s22, 0xff
	s_cbranch_scc1 .LBB0_651
	s_barrier

.LBB0_1184:
	v_readlane_b32 s64, v254, 21
	s_ashr_i32 s17, s16, 31
	v_readlane_b32 s65, v254, 22
	v_cmp_lt_i64_e32 vcc, s[18:19], v[216:217]
	s_lshl_b64 s[18:19], s[16:17], 20
	s_mov_b64 s[52:53], s[64:65]
	s_add_u32 s18, s52, s18
	s_addc_u32 s19, s53, s19
	s_and_b64 s[20:21], vcc, exec
	s_cselect_b32 s17, s19, s25
	s_cselect_b32 s31, s18, s24
	s_ashr_i32 s15, s14, 31
	s_lshl_b64 s[20:21], s[14:15], 20
	s_add_u32 s20, s36, s20
	s_addc_u32 s21, s37, s21
	s_and_b64 s[28:29], vcc, exec
	s_cselect_b32 s15, s21, s27
	s_cselect_b32 s61, s20, s26
	s_add_u32 s24, s24, 0x80080
	s_addc_u32 s25, s25, 0
	s_add_u32 s62, s26, 0x100
	v_mov_b32_e32 v0, 0
	s_addc_u32 s63, s27, 0
	s_mov_b32 s64, -2
	v_mov_b32_e32 v1, v0
	v_mov_b32_e32 v2, v0
	v_mov_b32_e32 v3, v0
	v_mov_b32_e32 v4, v0
	v_mov_b32_e32 v5, v0
	v_mov_b32_e32 v6, v0
	v_mov_b32_e32 v7, v0
	v_mov_b32_e32 v16, v0
	v_mov_b32_e32 v17, v0
	v_mov_b32_e32 v18, v0
	v_mov_b32_e32 v19, v0
	v_mov_b32_e32 v20, v0
	v_mov_b32_e32 v21, v0
	v_mov_b32_e32 v22, v0
	v_mov_b32_e32 v23, v0
	v_mov_b32_e32 v32, v0
	v_mov_b32_e32 v33, v0
	v_mov_b32_e32 v34, v0
	v_mov_b32_e32 v35, v0
	v_mov_b32_e32 v36, v0
	v_mov_b32_e32 v37, v0
	v_mov_b32_e32 v38, v0
	v_mov_b32_e32 v39, v0
	v_mov_b32_e32 v48, v0
	v_mov_b32_e32 v49, v0
	v_mov_b32_e32 v50, v0
	v_mov_b32_e32 v51, v0
	v_mov_b32_e32 v52, v0
	v_mov_b32_e32 v53, v0
	v_mov_b32_e32 v54, v0
	v_mov_b32_e32 v55, v0
	v_mov_b32_e32 v8, v0
	v_mov_b32_e32 v9, v0
	v_mov_b32_e32 v10, v0
	v_mov_b32_e32 v11, v0
	v_mov_b32_e32 v12, v0
	v_mov_b32_e32 v13, v0
	v_mov_b32_e32 v14, v0
	v_mov_b32_e32 v15, v0
	v_mov_b32_e32 v24, v0
	v_mov_b32_e32 v25, v0
	v_mov_b32_e32 v26, v0
	v_mov_b32_e32 v27, v0
	v_mov_b32_e32 v28, v0
	v_mov_b32_e32 v29, v0
	v_mov_b32_e32 v30, v0
	v_mov_b32_e32 v31, v0
	v_mov_b32_e32 v40, v0
	v_mov_b32_e32 v41, v0
	v_mov_b32_e32 v42, v0
	v_mov_b32_e32 v43, v0
	v_mov_b32_e32 v44, v0
	v_mov_b32_e32 v45, v0
	v_mov_b32_e32 v46, v0
	v_mov_b32_e32 v47, v0
	v_mov_b32_e32 v56, v0
	v_mov_b32_e32 v57, v0
	v_mov_b32_e32 v58, v0
	v_mov_b32_e32 v59, v0
	v_mov_b32_e32 v60, v0
	v_mov_b32_e32 v61, v0
	v_mov_b32_e32 v62, v0
	v_mov_b32_e32 v63, v0
	v_mov_b32_e32 v64, v0
	v_mov_b32_e32 v65, v0
	v_mov_b32_e32 v66, v0
	v_mov_b32_e32 v67, v0
	v_mov_b32_e32 v68, v0
	v_mov_b32_e32 v69, v0
	v_mov_b32_e32 v70, v0
	v_mov_b32_e32 v71, v0
	v_mov_b32_e32 v80, v0
	v_mov_b32_e32 v81, v0
	v_mov_b32_e32 v82, v0
	v_mov_b32_e32 v83, v0
	v_mov_b32_e32 v84, v0
	v_mov_b32_e32 v85, v0
	v_mov_b32_e32 v86, v0
	v_mov_b32_e32 v87, v0
	v_mov_b32_e32 v104, v0
	v_mov_b32_e32 v105, v0
	v_mov_b32_e32 v106, v0
	v_mov_b32_e32 v107, v0
	v_mov_b32_e32 v112, v0
	v_mov_b32_e32 v113, v0
	v_mov_b32_e32 v114, v0
	v_mov_b32_e32 v115, v0
	v_mov_b32_e32 v132, v0
	v_mov_b32_e32 v133, v0
	v_mov_b32_e32 v134, v0
	v_mov_b32_e32 v135, v0
	v_mov_b32_e32 v140, v0
	v_mov_b32_e32 v141, v0
	v_mov_b32_e32 v142, v0
	v_mov_b32_e32 v143, v0
	v_mov_b32_e32 v72, v0
	v_mov_b32_e32 v73, v0
	v_mov_b32_e32 v74, v0
	v_mov_b32_e32 v75, v0
	v_mov_b32_e32 v76, v0
	v_mov_b32_e32 v77, v0
	v_mov_b32_e32 v78, v0
	v_mov_b32_e32 v79, v0
	v_mov_b32_e32 v92, v0
	v_mov_b32_e32 v93, v0
	v_mov_b32_e32 v94, v0
	v_mov_b32_e32 v95, v0
	v_mov_b32_e32 v100, v0
	v_mov_b32_e32 v101, v0
	v_mov_b32_e32 v102, v0
	v_mov_b32_e32 v103, v0
	v_mov_b32_e32 v120, v0
	v_mov_b32_e32 v121, v0
	v_mov_b32_e32 v122, v0
	v_mov_b32_e32 v123, v0
	v_mov_b32_e32 v124, v0
	v_mov_b32_e32 v125, v0
	v_mov_b32_e32 v126, v0
	v_mov_b32_e32 v127, v0
	v_mov_b32_e32 v156, v0
	v_mov_b32_e32 v157, v0
	v_mov_b32_e32 v158, v0
	v_mov_b32_e32 v159, v0
	v_mov_b32_e32 v160, v0
	v_mov_b32_e32 v161, v0
	v_mov_b32_e32 v162, v0
	v_mov_b32_e32 v163, v0
	v_readlane_b32 s66, v254, 23
	v_readlane_b32 s67, v254, 24
	v_readlane_b32 s68, v254, 25
	v_readlane_b32 s69, v254, 26
	v_readlane_b32 s70, v254, 27
	v_readlane_b32 s71, v254, 28
	v_readlane_b32 s72, v254, 29
	v_readlane_b32 s73, v254, 30
	v_readlane_b32 s74, v254, 31
	v_readlane_b32 s75, v254, 32
	v_readlane_b32 s76, v254, 33
	v_readlane_b32 s77, v254, 34
	v_readlane_b32 s78, v254, 35
	v_readlane_b32 s79, v254, 36
	s_cmpk_gt_u32 s34, 0xff
	s_cbranch_scc0 .Lprio_k3
	s_setprio 1
.Lprio_k3:
.LBB0_1185:
	ds_read_b128 v[88:91], v243
	ds_read_b128 v[96:99], v243 offset:1024
	ds_read_b128 v[108:111], v243 offset:2048
	ds_read_b128 v[116:119], v243 offset:3072
	s_add_u32 s26, s24, 0xfff80080
	s_addc_u32 s27, s25, -1
	s_cmp_eq_u32 s64, 28
	s_cselect_b32 s29, s17, s27
	s_cselect_b32 s28, s31, s26
	s_cselect_b32 s27, s15, s63
	s_cselect_b32 s26, s61, s62
	v_lshl_add_u64 v[176:177], s[24:25], 0, v[212:213]
	s_add_i32 m0, s23, 0xc000
	ds_read_b128 v[128:131], v244
	ds_read_b128 v[136:139], v244 offset:1024
	ds_read_b128 v[144:147], v244 offset:2048
	ds_read_b128 v[148:151], v244 offset:3072
	ds_read_b128 v[152:155], v244 offset:4096
	ds_read_b128 v[164:167], v244 offset:5120
	ds_read_b128 v[168:171], v244 offset:6144
	ds_read_b128 v[172:175], v244 offset:7168
	global_load_lds_dwordx4 v[176:177], off
	v_lshl_add_u64 v[176:177], s[24:25], 0, v[214:215]
	s_add_i32 m0, s23, 0xe000
	s_nop 0
	global_load_lds_dwordx4 v[176:177], off
	s_waitcnt lgkmcnt(8)
	s_barrier
	s_waitcnt lgkmcnt(0)
	s_waitcnt lgkmcnt(0)
	v_mfma_f32_16x16x32_f16 v[160:163], v[88:91], v[128:131], v[160:163]
	v_mfma_f32_16x16x32_f16 v[156:159], v[108:111], v[128:131], v[156:159]
	v_mfma_f32_16x16x32_f16 v[124:127], v[88:91], v[144:147], v[124:127]
	v_mfma_f32_16x16x32_f16 v[120:123], v[108:111], v[144:147], v[120:123]
	v_mfma_f32_16x16x32_f16 v[100:103], v[88:91], v[152:155], v[100:103]
	v_mfma_f32_16x16x32_f16 v[92:95], v[108:111], v[152:155], v[92:95]
	v_mfma_f32_16x16x32_f16 v[76:79], v[88:91], v[168:171], v[76:79]
	v_mfma_f32_16x16x32_f16 v[72:75], v[108:111], v[168:171], v[72:75]
	v_mfma_f32_16x16x32_f16 v[160:163], v[96:99], v[136:139], v[160:163]
	v_mfma_f32_16x16x32_f16 v[156:159], v[116:119], v[136:139], v[156:159]
	v_mfma_f32_16x16x32_f16 v[124:127], v[96:99], v[148:151], v[124:127]
	v_mfma_f32_16x16x32_f16 v[120:123], v[116:119], v[148:151], v[120:123]
	v_mfma_f32_16x16x32_f16 v[100:103], v[96:99], v[164:167], v[100:103]
	v_mfma_f32_16x16x32_f16 v[92:95], v[116:119], v[164:167], v[92:95]
	v_mfma_f32_16x16x32_f16 v[76:79], v[96:99], v[172:175], v[76:79]
	v_mfma_f32_16x16x32_f16 v[72:75], v[116:119], v[172:175], v[72:75]
	s_barrier
	s_add_i32 s65, s59, s44
	v_lshl_add_u64 v[192:193], s[26:27], 0, v[206:207]
	s_mov_b32 m0, s65
	ds_read_b128 v[176:179], v245
	ds_read_b128 v[180:183], v245 offset:1024
	ds_read_b128 v[184:187], v245 offset:2048
	ds_read_b128 v[188:191], v245 offset:3072
	global_load_lds_dwordx4 v[192:193], off
	v_lshl_add_u64 v[194:195], s[26:27], 0, v[210:211]
	s_add_i32 m0, s65, 0x2000
	s_nop 0
	global_load_lds_dwordx4 v[194:195], off
	s_barrier
	s_waitcnt lgkmcnt(0)
	s_waitcnt lgkmcnt(0)
	v_mfma_f32_16x16x32_f16 v[140:143], v[176:179], v[128:131], v[140:143]
	v_mfma_f32_16x16x32_f16 v[112:115], v[176:179], v[144:147], v[112:115]
	v_mfma_f32_16x16x32_f16 v[104:107], v[184:187], v[144:147], v[104:107]
	v_mfma_f32_16x16x32_f16 v[84:87], v[176:179], v[152:155], v[84:87]
	v_mfma_f32_16x16x32_f16 v[80:83], v[184:187], v[152:155], v[80:83]
	v_mfma_f32_16x16x32_f16 v[68:71], v[176:179], v[168:171], v[68:71]
	v_mfma_f32_16x16x32_f16 v[64:67], v[184:187], v[168:171], v[64:67]
	v_mfma_f32_16x16x32_f16 v[140:143], v[180:183], v[136:139], v[140:143]
	v_mfma_f32_16x16x32_f16 v[128:131], v[184:187], v[128:131], v[132:135]
	v_mfma_f32_16x16x32_f16 v[112:115], v[180:183], v[148:151], v[112:115]
	v_mfma_f32_16x16x32_f16 v[104:107], v[188:191], v[148:151], v[104:107]
	v_mfma_f32_16x16x32_f16 v[84:87], v[180:183], v[164:167], v[84:87]
	v_mfma_f32_16x16x32_f16 v[80:83], v[188:191], v[164:167], v[80:83]
	v_mfma_f32_16x16x32_f16 v[68:71], v[180:183], v[172:175], v[68:71]
	v_mfma_f32_16x16x32_f16 v[64:67], v[188:191], v[172:175], v[64:67]
	v_mfma_f32_16x16x32_f16 v[128:131], v[188:191], v[136:139], v[128:131]
	s_mov_b32 m0, s23
	v_lshl_add_u64 v[196:197], s[28:29], 0, v[204:205]
	s_barrier
	ds_read_b128 v[132:135], v244 offset:16384
	ds_read_b128 v[136:139], v244 offset:17408
	ds_read_b128 v[144:147], v244 offset:18432
	ds_read_b128 v[148:151], v244 offset:19456
	ds_read_b128 v[152:155], v244 offset:20480
	ds_read_b128 v[164:167], v244 offset:21504
	ds_read_b128 v[168:171], v244 offset:22528
	ds_read_b128 v[172:175], v244 offset:23552
	global_load_lds_dwordx4 v[196:197], off
	v_lshl_add_u64 v[198:199], s[28:29], 0, v[208:209]
	s_mov_b32 m0, s45
	s_nop 0
	global_load_lds_dwordx4 v[198:199], off
	s_barrier
	s_waitcnt lgkmcnt(0)
	s_waitcnt lgkmcnt(0)
	v_mfma_f32_16x16x32_f16 v[60:63], v[88:91], v[132:135], v[60:63]
	v_mfma_f32_16x16x32_f16 v[56:59], v[108:111], v[132:135], v[56:59]
	v_mfma_f32_16x16x32_f16 v[44:47], v[88:91], v[144:147], v[44:47]
	v_mfma_f32_16x16x32_f16 v[40:43], v[108:111], v[144:147], v[40:43]
	v_mfma_f32_16x16x32_f16 v[28:31], v[88:91], v[152:155], v[28:31]
	v_mfma_f32_16x16x32_f16 v[24:27], v[108:111], v[152:155], v[24:27]
	v_mfma_f32_16x16x32_f16 v[12:15], v[88:91], v[168:171], v[12:15]
	v_mfma_f32_16x16x32_f16 v[8:11], v[108:111], v[168:171], v[8:11]
	v_mfma_f32_16x16x32_f16 v[60:63], v[96:99], v[136:139], v[60:63]
	v_mfma_f32_16x16x32_f16 v[56:59], v[116:119], v[136:139], v[56:59]
	v_mfma_f32_16x16x32_f16 v[44:47], v[96:99], v[148:151], v[44:47]
	v_mfma_f32_16x16x32_f16 v[40:43], v[116:119], v[148:151], v[40:43]
	v_mfma_f32_16x16x32_f16 v[28:31], v[96:99], v[164:167], v[28:31]
	v_mfma_f32_16x16x32_f16 v[24:27], v[116:119], v[164:167], v[24:27]
	v_mfma_f32_16x16x32_f16 v[12:15], v[96:99], v[172:175], v[12:15]
	v_mfma_f32_16x16x32_f16 v[8:11], v[116:119], v[172:175], v[8:11]
	s_barrier
	s_add_u32 s66, s26, 0x80000
	s_addc_u32 s67, s27, 0
	s_add_i32 s65, s60, s44
	v_lshl_add_u64 v[88:89], s[66:67], 0, v[206:207]
	s_mov_b32 m0, s65
	s_nop 0
	global_load_lds_dwordx4 v[88:89], off
	v_lshl_add_u64 v[88:89], s[66:67], 0, v[210:211]
	s_add_i32 m0, s65, 0x2000
	s_nop 0
	global_load_lds_dwordx4 v[88:89], off
	s_waitcnt vmcnt(6)
	s_barrier
	v_mfma_f32_16x16x32_f16 v[52:55], v[176:179], v[132:135], v[52:55]
	v_mfma_f32_16x16x32_f16 v[48:51], v[184:187], v[132:135], v[48:51]
	v_mfma_f32_16x16x32_f16 v[36:39], v[176:179], v[144:147], v[36:39]
	v_mfma_f32_16x16x32_f16 v[32:35], v[184:187], v[144:147], v[32:35]
	v_mfma_f32_16x16x32_f16 v[20:23], v[176:179], v[152:155], v[20:23]
	v_mfma_f32_16x16x32_f16 v[16:19], v[184:187], v[152:155], v[16:19]
	v_mfma_f32_16x16x32_f16 v[4:7], v[176:179], v[168:171], v[4:7]
	v_mfma_f32_16x16x32_f16 v[0:3], v[184:187], v[168:171], v[0:3]
	v_mfma_f32_16x16x32_f16 v[52:55], v[180:183], v[136:139], v[52:55]
	v_mfma_f32_16x16x32_f16 v[48:51], v[188:191], v[136:139], v[48:51]
	v_mfma_f32_16x16x32_f16 v[36:39], v[180:183], v[148:151], v[36:39]
	v_mfma_f32_16x16x32_f16 v[32:35], v[188:191], v[148:151], v[32:35]
	v_mfma_f32_16x16x32_f16 v[20:23], v[180:183], v[164:167], v[20:23]
	v_mfma_f32_16x16x32_f16 v[16:19], v[188:191], v[164:167], v[16:19]
	v_mfma_f32_16x16x32_f16 v[4:7], v[180:183], v[172:175], v[4:7]
	v_mfma_f32_16x16x32_f16 v[0:3], v[188:191], v[172:175], v[0:3]
	s_add_i32 s65, 0, 0x18000
	v_add_u32_e32 v116, s65, v241
	s_barrier
	ds_read_b128 v[88:91], v116
	ds_read_b128 v[96:99], v116 offset:1024
	ds_read_b128 v[108:111], v116 offset:2048
	ds_read_b128 v[116:119], v116 offset:3072
	s_add_u32 s28, s28, 0x80000
	s_addc_u32 s29, s29, 0
	s_mov_b32 m0, s48
	v_lshl_add_u64 v[176:177], s[28:29], 0, v[204:205]
	ds_read_b128 v[132:135], v244 offset:32768
	ds_read_b128 v[136:139], v244 offset:33792
	ds_read_b128 v[144:147], v244 offset:34816
	ds_read_b128 v[148:151], v244 offset:35840
	ds_read_b128 v[152:155], v244 offset:36864
	ds_read_b128 v[164:167], v244 offset:37888
	ds_read_b128 v[168:171], v244 offset:38912
	ds_read_b128 v[172:175], v244 offset:39936
	global_load_lds_dwordx4 v[176:177], off
	v_lshl_add_u64 v[176:177], s[28:29], 0, v[208:209]
	s_mov_b32 m0, s49
	s_nop 0
	global_load_lds_dwordx4 v[176:177], off
	s_waitcnt lgkmcnt(8)
	s_barrier
	s_waitcnt lgkmcnt(0)
	s_waitcnt lgkmcnt(0)
	v_mfma_f32_16x16x32_f16 v[160:163], v[88:91], v[132:135], v[160:163]
	v_mfma_f32_16x16x32_f16 v[156:159], v[108:111], v[132:135], v[156:159]
	v_mfma_f32_16x16x32_f16 v[124:127], v[88:91], v[144:147], v[124:127]
	v_mfma_f32_16x16x32_f16 v[120:123], v[108:111], v[144:147], v[120:123]
	v_mfma_f32_16x16x32_f16 v[100:103], v[88:91], v[152:155], v[100:103]
	v_mfma_f32_16x16x32_f16 v[92:95], v[108:111], v[152:155], v[92:95]
	v_mfma_f32_16x16x32_f16 v[76:79], v[88:91], v[168:171], v[76:79]
	v_mfma_f32_16x16x32_f16 v[72:75], v[108:111], v[168:171], v[72:75]
	v_mfma_f32_16x16x32_f16 v[160:163], v[96:99], v[136:139], v[160:163]
	v_mfma_f32_16x16x32_f16 v[156:159], v[116:119], v[136:139], v[156:159]
	v_mfma_f32_16x16x32_f16 v[124:127], v[96:99], v[148:151], v[124:127]
	v_mfma_f32_16x16x32_f16 v[120:123], v[116:119], v[148:151], v[120:123]
	v_mfma_f32_16x16x32_f16 v[100:103], v[96:99], v[164:167], v[100:103]
	v_mfma_f32_16x16x32_f16 v[92:95], v[116:119], v[164:167], v[92:95]
	v_mfma_f32_16x16x32_f16 v[76:79], v[96:99], v[172:175], v[76:79]
	v_mfma_f32_16x16x32_f16 v[72:75], v[116:119], v[172:175], v[72:75]
	s_barrier
	s_add_i32 s28, 0, 0x1c000
	s_add_i32 s29, s65, s44
	v_add_u32_e32 v188, s28, v241
	v_lshl_add_u64 v[192:193], v[192:193], 0, s[6:7]
	s_mov_b32 m0, s29
	ds_read_b128 v[176:179], v188
	ds_read_b128 v[180:183], v188 offset:1024
	ds_read_b128 v[184:187], v188 offset:2048
	ds_read_b128 v[188:191], v188 offset:3072
	global_load_lds_dwordx4 v[192:193], off
	v_lshl_add_u64 v[192:193], v[194:195], 0, s[6:7]
	s_add_i32 m0, s29, 0x2000
	s_nop 0
	global_load_lds_dwordx4 v[192:193], off
	s_barrier
	s_waitcnt lgkmcnt(0)
	s_waitcnt lgkmcnt(0)
	v_mfma_f32_16x16x32_f16 v[140:143], v[176:179], v[132:135], v[140:143]
	v_mfma_f32_16x16x32_f16 v[128:131], v[184:187], v[132:135], v[128:131]
	v_mfma_f32_16x16x32_f16 v[112:115], v[176:179], v[144:147], v[112:115]
	v_mfma_f32_16x16x32_f16 v[104:107], v[184:187], v[144:147], v[104:107]
	v_mfma_f32_16x16x32_f16 v[84:87], v[176:179], v[152:155], v[84:87]
	v_mfma_f32_16x16x32_f16 v[80:83], v[184:187], v[152:155], v[80:83]
	v_mfma_f32_16x16x32_f16 v[68:71], v[176:179], v[168:171], v[68:71]
	v_mfma_f32_16x16x32_f16 v[64:67], v[184:187], v[168:171], v[64:67]
	v_mfma_f32_16x16x32_f16 v[140:143], v[180:183], v[136:139], v[140:143]
	v_mfma_f32_16x16x32_f16 v[132:135], v[188:191], v[136:139], v[128:131]
	v_mfma_f32_16x16x32_f16 v[112:115], v[180:183], v[148:151], v[112:115]
	v_mfma_f32_16x16x32_f16 v[104:107], v[188:191], v[148:151], v[104:107]
	v_mfma_f32_16x16x32_f16 v[84:87], v[180:183], v[164:167], v[84:87]
	v_mfma_f32_16x16x32_f16 v[80:83], v[188:191], v[164:167], v[80:83]
	v_mfma_f32_16x16x32_f16 v[68:71], v[180:183], v[172:175], v[68:71]
	v_mfma_f32_16x16x32_f16 v[64:67], v[188:191], v[172:175], v[64:67]
	s_mov_b32 m0, s51
	v_lshl_add_u64 v[192:193], v[196:197], 0, s[6:7]
	s_barrier
	ds_read_b128 v[128:131], v244 offset:49152
	ds_read_b128 v[136:139], v244 offset:50176
	ds_read_b128 v[144:147], v244 offset:51200
	ds_read_b128 v[148:151], v244 offset:52224
	ds_read_b128 v[152:155], v244 offset:53248
	ds_read_b128 v[164:167], v244 offset:54272
	ds_read_b128 v[168:171], v244 offset:55296
	ds_read_b128 v[172:175], v244 offset:56320
	global_load_lds_dwordx4 v[192:193], off
	v_lshl_add_u64 v[192:193], v[198:199], 0, s[6:7]
	s_mov_b32 m0, s54
	s_nop 0
	global_load_lds_dwordx4 v[192:193], off
	s_barrier
	s_waitcnt lgkmcnt(0)
	s_waitcnt lgkmcnt(0)
	v_mfma_f32_16x16x32_f16 v[60:63], v[88:91], v[128:131], v[60:63]
	v_mfma_f32_16x16x32_f16 v[56:59], v[108:111], v[128:131], v[56:59]
	v_mfma_f32_16x16x32_f16 v[44:47], v[88:91], v[144:147], v[44:47]
	v_mfma_f32_16x16x32_f16 v[40:43], v[108:111], v[144:147], v[40:43]
	v_mfma_f32_16x16x32_f16 v[28:31], v[88:91], v[152:155], v[28:31]
	v_mfma_f32_16x16x32_f16 v[24:27], v[108:111], v[152:155], v[24:27]
	v_mfma_f32_16x16x32_f16 v[12:15], v[88:91], v[168:171], v[12:15]
	v_mfma_f32_16x16x32_f16 v[8:11], v[108:111], v[168:171], v[8:11]
	v_mfma_f32_16x16x32_f16 v[60:63], v[96:99], v[136:139], v[60:63]
	v_mfma_f32_16x16x32_f16 v[56:59], v[116:119], v[136:139], v[56:59]
	v_mfma_f32_16x16x32_f16 v[44:47], v[96:99], v[148:151], v[44:47]
	v_mfma_f32_16x16x32_f16 v[40:43], v[116:119], v[148:151], v[40:43]
	v_mfma_f32_16x16x32_f16 v[28:31], v[96:99], v[164:167], v[28:31]
	v_mfma_f32_16x16x32_f16 v[24:27], v[116:119], v[164:167], v[24:27]
	v_mfma_f32_16x16x32_f16 v[12:15], v[96:99], v[172:175], v[12:15]
	v_mfma_f32_16x16x32_f16 v[8:11], v[116:119], v[172:175], v[8:11]
	s_barrier
	s_add_u32 s26, s26, 0x80080
	s_addc_u32 s27, s27, 0
	s_add_i32 s28, s28, s44
	v_lshl_add_u64 v[88:89], s[26:27], 0, v[206:207]
	s_mov_b32 m0, s28
	s_nop 0
	global_load_lds_dwordx4 v[88:89], off
	v_lshl_add_u64 v[88:89], s[26:27], 0, v[210:211]
	s_add_i32 m0, s28, 0x2000
	s_nop 0
	global_load_lds_dwordx4 v[88:89], off
	s_waitcnt vmcnt(6)
	s_barrier
	v_mfma_f32_16x16x32_f16 v[52:55], v[176:179], v[128:131], v[52:55]
	v_mfma_f32_16x16x32_f16 v[48:51], v[184:187], v[128:131], v[48:51]
	v_mfma_f32_16x16x32_f16 v[36:39], v[176:179], v[144:147], v[36:39]
	v_mfma_f32_16x16x32_f16 v[32:35], v[184:187], v[144:147], v[32:35]
	v_mfma_f32_16x16x32_f16 v[20:23], v[176:179], v[152:155], v[20:23]
	v_mfma_f32_16x16x32_f16 v[16:19], v[184:187], v[152:155], v[16:19]
	v_mfma_f32_16x16x32_f16 v[4:7], v[176:179], v[168:171], v[4:7]
	v_mfma_f32_16x16x32_f16 v[0:3], v[184:187], v[168:171], v[0:3]
	v_mfma_f32_16x16x32_f16 v[52:55], v[180:183], v[136:139], v[52:55]
	v_mfma_f32_16x16x32_f16 v[48:51], v[188:191], v[136:139], v[48:51]
	v_mfma_f32_16x16x32_f16 v[36:39], v[180:183], v[148:151], v[36:39]
	v_mfma_f32_16x16x32_f16 v[32:35], v[188:191], v[148:151], v[32:35]
	v_mfma_f32_16x16x32_f16 v[20:23], v[180:183], v[164:167], v[20:23]
	v_mfma_f32_16x16x32_f16 v[16:19], v[188:191], v[164:167], v[16:19]
	v_mfma_f32_16x16x32_f16 v[4:7], v[180:183], v[172:175], v[4:7]
	v_mfma_f32_16x16x32_f16 v[0:3], v[188:191], v[172:175], v[0:3]
	s_add_i32 s64, s64, 2
	s_add_u32 s24, s24, 0x100
	s_addc_u32 s25, s25, 0
	s_add_u32 s62, s62, 0x100
	s_addc_u32 s63, s63, 0
	s_cmp_gt_u32 s64, 29
	s_barrier
	s_cbranch_scc0 .LBB0_1185
	s_setprio 0
	s_lshl_b32 s15, s22, 8
	s_add_i32 s17, s15, 0xffffe000
	s_lshr_b32 s17, s17, 11
	s_mulk_i32 s17, 0x1800
	s_addk_i32 s17, 0x1800
	s_cmp_gt_i32 s22, 31
	s_cselect_b32 s24, s17, 0
	s_ashr_i32 s25, s24, 31
	v_lshl_or_b32 v128, s30, 8, v242
	s_lshl_b64 s[24:25], s[24:25], 2
	s_add_u32 s24, s42, s24
	v_ashrrev_i32_e32 v129, 31, v128
	v_add_u32_e32 v130, s15, v240
	s_addc_u32 s25, s43, s25
	v_lshlrev_b64 v[220:221], 1, v[128:129]
	v_ashrrev_i32_e32 v131, 31, v130
	v_lshl_add_u64 v[96:97], v[128:129], 2, s[24:25]
	v_lshl_add_u64 v[128:129], s[4:5], 0, v[220:221]
	v_lshlrev_b64 v[236:237], 12, v[130:131]
	v_lshl_add_u64 v[136:137], v[128:129], 0, v[236:237]
	global_load_dwordx4 v[108:111], v[96:97], off offset:16
	global_load_dwordx4 v[116:119], v[96:97], off
	global_load_dwordx4 v[88:91], v[96:97], off offset:528
	s_nop 0
	global_load_dwordx4 v[96:99], v[96:97], off offset:512
	s_nop 0
	global_load_dwordx4 v[246:249], v[136:137], off nt
	global_load_dwordx4 v[200:203], v[136:137], off offset:256 nt
	v_or_b32_e32 v136, 16, v130
	v_ashrrev_i32_e32 v137, 31, v136
	v_lshlrev_b64 v[234:235], 12, v[136:137]
	v_lshl_add_u64 v[136:137], v[128:129], 0, v[234:235]
	global_load_dwordx4 v[196:199], v[136:137], off nt
	global_load_dwordx4 v[192:195], v[136:137], off offset:256 nt
	v_or_b32_e32 v136, 32, v130
	v_ashrrev_i32_e32 v137, 31, v136
	v_lshlrev_b64 v[232:233], 12, v[136:137]
	v_lshl_add_u64 v[136:137], v[128:129], 0, v[232:233]
	global_load_dwordx4 v[188:191], v[136:137], off nt
	global_load_dwordx4 v[184:187], v[136:137], off offset:256 nt
	v_readlane_b32 s64, v254, 21
	v_readlane_b32 s68, v254, 25
	v_readlane_b32 s69, v254, 26
	s_mov_b64 s[56:57], s[68:69]
	v_or_b32_e32 v130, 48, v130
	v_ashrrev_i32_e32 v131, 31, v130
	v_lshlrev_b64 v[230:231], 12, v[130:131]
	v_lshl_add_u64 v[130:131], v[128:129], 0, v[230:231]
	global_load_dwordx4 v[180:183], v[130:131], off nt
	global_load_dwordx4 v[176:179], v[130:131], off offset:256 nt
	v_lshl_add_u64 v[228:229], v[236:237], 0, s[0:1]
	v_lshl_add_u64 v[130:131], v[128:129], 0, v[228:229]
	global_load_dwordx4 v[172:175], v[130:131], off nt
	global_load_dwordx4 v[168:171], v[130:131], off offset:256 nt
	v_lshl_add_u64 v[226:227], v[236:237], 0, s[8:9]
	v_lshl_add_u64 v[130:131], v[128:129], 0, v[226:227]
	global_load_dwordx4 v[164:167], v[130:131], off nt
	global_load_dwordx4 v[152:155], v[130:131], off offset:256 nt
	v_lshl_add_u64 v[224:225], v[236:237], 0, s[10:11]
	v_lshl_add_u64 v[130:131], v[128:129], 0, v[224:225]
	global_load_dwordx4 v[148:151], v[130:131], off nt
	global_load_dwordx4 v[144:147], v[130:131], off offset:256 nt
	v_lshl_add_u64 v[222:223], v[236:237], 0, s[12:13]
	v_lshl_add_u64 v[128:129], v[128:129], 0, v[222:223]
	global_load_dwordx4 v[136:139], v[128:129], off nt
	s_nop 0
	global_load_dwordx4 v[128:131], v[128:129], off offset:256 nt
	s_and_b64 vcc, exec, s[2:3]
	s_mov_b32 s30, s14
	s_mov_b32 s22, s16
	s_mov_b64 s[26:27], s[20:21]
	s_mov_b64 s[24:25], s[18:19]
	v_readlane_b32 s65, v254, 22
	v_readlane_b32 s66, v254, 23
	v_readlane_b32 s67, v254, 24
	v_readlane_b32 s70, v254, 27
	v_readlane_b32 s71, v254, 28
	v_readlane_b32 s72, v254, 29
	v_readlane_b32 s73, v254, 30
	v_readlane_b32 s74, v254, 31
	v_readlane_b32 s75, v254, 32
	v_readlane_b32 s76, v254, 33
	v_readlane_b32 s77, v254, 34
	v_readlane_b32 s78, v254, 35
	v_readlane_b32 s79, v254, 36
	s_waitcnt vmcnt(0)
	v_cvt_f32_f16_e32 v250, v246
	v_cvt_f32_f16_sdwa v251, v246 dst_sel:DWORD dst_unused:UNUSED_PAD src0_sel:WORD_1
	v_pk_fma_f32 v[160:161], v[160:161], v[116:117], v[250:251]
	s_nop 0
	v_cvt_pk_f16_f32 v246, v160, v161
	v_cvt_f32_f16_e32 v160, v248
	v_cvt_f32_f16_sdwa v161, v248 dst_sel:DWORD dst_unused:UNUSED_PAD src0_sel:WORD_1
	v_pk_fma_f32 v[156:157], v[156:157], v[108:109], v[160:161]
	s_nop 0
	v_cvt_pk_f16_f32 v248, v156, v157
	v_cvt_f32_f16_e32 v156, v247
	v_cvt_f32_f16_sdwa v157, v247 dst_sel:DWORD dst_unused:UNUSED_PAD src0_sel:WORD_1
	v_pk_fma_f32 v[156:157], v[162:163], v[118:119], v[156:157]
	s_nop 0
	v_cvt_pk_f16_f32 v247, v156, v157
	v_cvt_f32_f16_e32 v156, v249
	v_cvt_f32_f16_sdwa v157, v249 dst_sel:DWORD dst_unused:UNUSED_PAD src0_sel:WORD_1
	v_pk_fma_f32 v[156:157], v[158:159], v[110:111], v[156:157]
	s_nop 0
	v_cvt_pk_f16_f32 v249, v156, v157
	v_lshl_add_u64 v[156:157], s[56:57], 0, v[236:237]
	v_lshl_add_u64 v[160:161], v[156:157], 0, v[220:221]
	v_cvt_f32_f16_e32 v156, v200
	v_cvt_f32_f16_sdwa v157, v200 dst_sel:DWORD dst_unused:UNUSED_PAD src0_sel:WORD_1
	global_store_dwordx4 v[160:161], v[246:249], off
	v_pk_fma_f32 v[140:141], v[140:141], v[96:97], v[156:157]
	s_nop 0
	v_cvt_pk_f16_f32 v156, v140, v141
	v_cvt_f32_f16_e32 v140, v202
	v_cvt_f32_f16_sdwa v141, v202 dst_sel:DWORD dst_unused:UNUSED_PAD src0_sel:WORD_1
	v_pk_fma_f32 v[132:133], v[132:133], v[88:89], v[140:141]
	s_nop 0
	v_cvt_pk_f16_f32 v158, v132, v133
	v_cvt_f32_f16_e32 v132, v201
	v_cvt_f32_f16_sdwa v133, v201 dst_sel:DWORD dst_unused:UNUSED_PAD src0_sel:WORD_1
	v_pk_fma_f32 v[132:133], v[142:143], v[98:99], v[132:133]
	s_nop 0
	v_cvt_pk_f16_f32 v157, v132, v133
	v_cvt_f32_f16_e32 v132, v203
	v_cvt_f32_f16_sdwa v133, v203 dst_sel:DWORD dst_unused:UNUSED_PAD src0_sel:WORD_1
	v_pk_fma_f32 v[132:133], v[134:135], v[90:91], v[132:133]
	s_nop 0
	v_cvt_pk_f16_f32 v159, v132, v133
	v_cvt_f32_f16_e32 v132, v196
	v_cvt_f32_f16_sdwa v133, v196 dst_sel:DWORD dst_unused:UNUSED_PAD src0_sel:WORD_1
	global_store_dwordx4 v[160:161], v[156:159], off offset:256
	v_pk_fma_f32 v[124:125], v[124:125], v[116:117], v[132:133]
	s_nop 0
	v_cvt_pk_f16_f32 v132, v124, v125
	v_cvt_f32_f16_e32 v124, v198
	v_cvt_f32_f16_sdwa v125, v198 dst_sel:DWORD dst_unused:UNUSED_PAD src0_sel:WORD_1
	v_pk_fma_f32 v[120:121], v[120:121], v[108:109], v[124:125]
	s_nop 0
	v_cvt_pk_f16_f32 v134, v120, v121
	v_cvt_f32_f16_e32 v120, v197
	v_cvt_f32_f16_sdwa v121, v197 dst_sel:DWORD dst_unused:UNUSED_PAD src0_sel:WORD_1
	v_pk_fma_f32 v[120:121], v[126:127], v[118:119], v[120:121]
	s_nop 0
	v_cvt_pk_f16_f32 v133, v120, v121
	v_cvt_f32_f16_e32 v120, v199
	v_cvt_f32_f16_sdwa v121, v199 dst_sel:DWORD dst_unused:UNUSED_PAD src0_sel:WORD_1
	v_pk_fma_f32 v[120:121], v[122:123], v[110:111], v[120:121]
	s_nop 0
	v_cvt_pk_f16_f32 v135, v120, v121
	v_lshl_add_u64 v[120:121], s[56:57], 0, v[234:235]
	v_lshl_add_u64 v[124:125], v[120:121], 0, v[220:221]
	v_cvt_f32_f16_e32 v120, v192
	v_cvt_f32_f16_sdwa v121, v192 dst_sel:DWORD dst_unused:UNUSED_PAD src0_sel:WORD_1
	global_store_dwordx4 v[124:125], v[132:135], off
	v_pk_fma_f32 v[112:113], v[112:113], v[96:97], v[120:121]
	s_nop 0
	v_cvt_pk_f16_f32 v120, v112, v113
	v_cvt_f32_f16_e32 v112, v194
	v_cvt_f32_f16_sdwa v113, v194 dst_sel:DWORD dst_unused:UNUSED_PAD src0_sel:WORD_1
	v_pk_fma_f32 v[104:105], v[104:105], v[88:89], v[112:113]
	s_nop 0
	v_cvt_pk_f16_f32 v122, v104, v105
	v_cvt_f32_f16_e32 v104, v193
	v_cvt_f32_f16_sdwa v105, v193 dst_sel:DWORD dst_unused:UNUSED_PAD src0_sel:WORD_1
	v_pk_fma_f32 v[104:105], v[114:115], v[98:99], v[104:105]
	s_nop 0
	v_cvt_pk_f16_f32 v121, v104, v105
	v_cvt_f32_f16_e32 v104, v195
	v_cvt_f32_f16_sdwa v105, v195 dst_sel:DWORD dst_unused:UNUSED_PAD src0_sel:WORD_1
	v_pk_fma_f32 v[104:105], v[106:107], v[90:91], v[104:105]
	s_nop 0
	v_cvt_pk_f16_f32 v123, v104, v105
	v_cvt_f32_f16_e32 v104, v188
	v_cvt_f32_f16_sdwa v105, v188 dst_sel:DWORD dst_unused:UNUSED_PAD src0_sel:WORD_1
	global_store_dwordx4 v[124:125], v[120:123], off offset:256
	v_pk_fma_f32 v[100:101], v[100:101], v[116:117], v[104:105]
	s_nop 0
	v_cvt_pk_f16_f32 v104, v100, v101
	v_cvt_f32_f16_e32 v100, v190
	v_cvt_f32_f16_sdwa v101, v190 dst_sel:DWORD dst_unused:UNUSED_PAD src0_sel:WORD_1
	v_pk_fma_f32 v[92:93], v[92:93], v[108:109], v[100:101]
	s_nop 0
	v_cvt_pk_f16_f32 v106, v92, v93
	v_cvt_f32_f16_e32 v92, v189
	v_cvt_f32_f16_sdwa v93, v189 dst_sel:DWORD dst_unused:UNUSED_PAD src0_sel:WORD_1
	v_pk_fma_f32 v[92:93], v[102:103], v[118:119], v[92:93]
	s_nop 0
	v_cvt_pk_f16_f32 v105, v92, v93
	v_cvt_f32_f16_e32 v92, v191
	v_cvt_f32_f16_sdwa v93, v191 dst_sel:DWORD dst_unused:UNUSED_PAD src0_sel:WORD_1
	v_pk_fma_f32 v[92:93], v[94:95], v[110:111], v[92:93]
	s_nop 0
	v_cvt_pk_f16_f32 v107, v92, v93
	v_lshl_add_u64 v[92:93], s[56:57], 0, v[232:233]
	v_lshl_add_u64 v[100:101], v[92:93], 0, v[220:221]
	v_cvt_f32_f16_e32 v92, v184
	v_cvt_f32_f16_sdwa v93, v184 dst_sel:DWORD dst_unused:UNUSED_PAD src0_sel:WORD_1
	global_store_dwordx4 v[100:101], v[104:107], off
	v_pk_fma_f32 v[84:85], v[84:85], v[96:97], v[92:93]
	s_nop 0
	v_cvt_pk_f16_f32 v92, v84, v85
	v_cvt_f32_f16_e32 v84, v186
	v_cvt_f32_f16_sdwa v85, v186 dst_sel:DWORD dst_unused:UNUSED_PAD src0_sel:WORD_1
	v_pk_fma_f32 v[80:81], v[80:81], v[88:89], v[84:85]
	s_nop 0
	v_cvt_pk_f16_f32 v94, v80, v81
	v_cvt_f32_f16_e32 v80, v185
	v_cvt_f32_f16_sdwa v81, v185 dst_sel:DWORD dst_unused:UNUSED_PAD src0_sel:WORD_1
	v_pk_fma_f32 v[80:81], v[86:87], v[98:99], v[80:81]
	s_nop 0
	v_cvt_pk_f16_f32 v93, v80, v81
	v_cvt_f32_f16_e32 v80, v187
	v_cvt_f32_f16_sdwa v81, v187 dst_sel:DWORD dst_unused:UNUSED_PAD src0_sel:WORD_1
	v_pk_fma_f32 v[80:81], v[82:83], v[90:91], v[80:81]
	s_nop 0
	v_cvt_pk_f16_f32 v95, v80, v81
	v_cvt_f32_f16_e32 v80, v180
	v_cvt_f32_f16_sdwa v81, v180 dst_sel:DWORD dst_unused:UNUSED_PAD src0_sel:WORD_1
	global_store_dwordx4 v[100:101], v[92:95], off offset:256
	v_pk_fma_f32 v[76:77], v[76:77], v[116:117], v[80:81]
	s_nop 0
	v_cvt_pk_f16_f32 v80, v76, v77
	v_cvt_f32_f16_e32 v76, v182
	v_cvt_f32_f16_sdwa v77, v182 dst_sel:DWORD dst_unused:UNUSED_PAD src0_sel:WORD_1
	v_pk_fma_f32 v[72:73], v[72:73], v[108:109], v[76:77]
	s_nop 0
	v_cvt_pk_f16_f32 v82, v72, v73
	v_cvt_f32_f16_e32 v72, v181
	v_cvt_f32_f16_sdwa v73, v181 dst_sel:DWORD dst_unused:UNUSED_PAD src0_sel:WORD_1
	v_pk_fma_f32 v[72:73], v[78:79], v[118:119], v[72:73]
	s_nop 0
	v_cvt_pk_f16_f32 v81, v72, v73
	v_cvt_f32_f16_e32 v72, v183
	v_cvt_f32_f16_sdwa v73, v183 dst_sel:DWORD dst_unused:UNUSED_PAD src0_sel:WORD_1
	v_pk_fma_f32 v[72:73], v[74:75], v[110:111], v[72:73]
	s_nop 0
	v_cvt_pk_f16_f32 v83, v72, v73
	v_lshl_add_u64 v[72:73], s[56:57], 0, v[230:231]
	v_lshl_add_u64 v[76:77], v[72:73], 0, v[220:221]
	v_cvt_f32_f16_e32 v72, v176
	v_cvt_f32_f16_sdwa v73, v176 dst_sel:DWORD dst_unused:UNUSED_PAD src0_sel:WORD_1
	global_store_dwordx4 v[76:77], v[80:83], off
	v_pk_fma_f32 v[68:69], v[68:69], v[96:97], v[72:73]
	s_nop 0
	v_cvt_pk_f16_f32 v72, v68, v69
	v_cvt_f32_f16_e32 v68, v178
	v_cvt_f32_f16_sdwa v69, v178 dst_sel:DWORD dst_unused:UNUSED_PAD src0_sel:WORD_1
	v_pk_fma_f32 v[64:65], v[64:65], v[88:89], v[68:69]
	s_nop 0
	v_cvt_pk_f16_f32 v74, v64, v65
	v_cvt_f32_f16_e32 v64, v177
	v_cvt_f32_f16_sdwa v65, v177 dst_sel:DWORD dst_unused:UNUSED_PAD src0_sel:WORD_1
	v_pk_fma_f32 v[64:65], v[70:71], v[98:99], v[64:65]
	s_nop 0
	v_cvt_pk_f16_f32 v73, v64, v65
	v_cvt_f32_f16_e32 v64, v179
	v_cvt_f32_f16_sdwa v65, v179 dst_sel:DWORD dst_unused:UNUSED_PAD src0_sel:WORD_1
	v_pk_fma_f32 v[64:65], v[66:67], v[90:91], v[64:65]
	s_nop 0
	v_cvt_pk_f16_f32 v75, v64, v65
	v_cvt_f32_f16_e32 v64, v172
	v_cvt_f32_f16_sdwa v65, v172 dst_sel:DWORD dst_unused:UNUSED_PAD src0_sel:WORD_1
	global_store_dwordx4 v[76:77], v[72:75], off offset:256
	v_pk_fma_f32 v[60:61], v[60:61], v[116:117], v[64:65]
	s_nop 0
	v_cvt_pk_f16_f32 v64, v60, v61
	v_cvt_f32_f16_e32 v60, v174
	v_cvt_f32_f16_sdwa v61, v174 dst_sel:DWORD dst_unused:UNUSED_PAD src0_sel:WORD_1
	v_pk_fma_f32 v[56:57], v[56:57], v[108:109], v[60:61]
	s_nop 0
	v_cvt_pk_f16_f32 v66, v56, v57
	v_cvt_f32_f16_e32 v56, v173
	v_cvt_f32_f16_sdwa v57, v173 dst_sel:DWORD dst_unused:UNUSED_PAD src0_sel:WORD_1
	v_pk_fma_f32 v[56:57], v[62:63], v[118:119], v[56:57]
	s_nop 0
	v_cvt_pk_f16_f32 v65, v56, v57
	v_cvt_f32_f16_e32 v56, v175
	v_cvt_f32_f16_sdwa v57, v175 dst_sel:DWORD dst_unused:UNUSED_PAD src0_sel:WORD_1
	v_pk_fma_f32 v[56:57], v[58:59], v[110:111], v[56:57]
	s_nop 0
	v_cvt_pk_f16_f32 v67, v56, v57
	v_lshl_add_u64 v[56:57], s[56:57], 0, v[228:229]
	v_lshl_add_u64 v[60:61], v[56:57], 0, v[220:221]
	v_cvt_f32_f16_e32 v56, v168
	v_cvt_f32_f16_sdwa v57, v168 dst_sel:DWORD dst_unused:UNUSED_PAD src0_sel:WORD_1
	global_store_dwordx4 v[60:61], v[64:67], off
	v_pk_fma_f32 v[52:53], v[52:53], v[96:97], v[56:57]
	s_nop 0
	v_cvt_pk_f16_f32 v56, v52, v53
	v_cvt_f32_f16_e32 v52, v170
	v_cvt_f32_f16_sdwa v53, v170 dst_sel:DWORD dst_unused:UNUSED_PAD src0_sel:WORD_1
	v_pk_fma_f32 v[48:49], v[48:49], v[88:89], v[52:53]
	s_nop 0
	v_cvt_pk_f16_f32 v58, v48, v49
	v_cvt_f32_f16_e32 v48, v169
	v_cvt_f32_f16_sdwa v49, v169 dst_sel:DWORD dst_unused:UNUSED_PAD src0_sel:WORD_1
	v_pk_fma_f32 v[48:49], v[54:55], v[98:99], v[48:49]
	s_nop 0
	v_cvt_pk_f16_f32 v57, v48, v49
	v_cvt_f32_f16_e32 v48, v171
	v_cvt_f32_f16_sdwa v49, v171 dst_sel:DWORD dst_unused:UNUSED_PAD src0_sel:WORD_1
	v_pk_fma_f32 v[48:49], v[50:51], v[90:91], v[48:49]
	s_nop 0
	v_cvt_pk_f16_f32 v59, v48, v49
	v_cvt_f32_f16_e32 v48, v164
	v_cvt_f32_f16_sdwa v49, v164 dst_sel:DWORD dst_unused:UNUSED_PAD src0_sel:WORD_1
	global_store_dwordx4 v[60:61], v[56:59], off offset:256
	v_pk_fma_f32 v[44:45], v[44:45], v[116:117], v[48:49]
	s_nop 0
	v_cvt_pk_f16_f32 v48, v44, v45
	v_cvt_f32_f16_e32 v44, v166
	v_cvt_f32_f16_sdwa v45, v166 dst_sel:DWORD dst_unused:UNUSED_PAD src0_sel:WORD_1
	v_pk_fma_f32 v[40:41], v[40:41], v[108:109], v[44:45]
	s_nop 0
	v_cvt_pk_f16_f32 v50, v40, v41
	v_cvt_f32_f16_e32 v40, v165
	v_cvt_f32_f16_sdwa v41, v165 dst_sel:DWORD dst_unused:UNUSED_PAD src0_sel:WORD_1
	v_pk_fma_f32 v[40:41], v[46:47], v[118:119], v[40:41]
	s_nop 0
	v_cvt_pk_f16_f32 v49, v40, v41
	v_cvt_f32_f16_e32 v40, v167
	v_cvt_f32_f16_sdwa v41, v167 dst_sel:DWORD dst_unused:UNUSED_PAD src0_sel:WORD_1
	v_pk_fma_f32 v[40:41], v[42:43], v[110:111], v[40:41]
	s_nop 0
	v_cvt_pk_f16_f32 v51, v40, v41
	v_lshl_add_u64 v[40:41], s[56:57], 0, v[226:227]
	v_lshl_add_u64 v[44:45], v[40:41], 0, v[220:221]
	v_cvt_f32_f16_e32 v40, v152
	v_cvt_f32_f16_sdwa v41, v152 dst_sel:DWORD dst_unused:UNUSED_PAD src0_sel:WORD_1
	global_store_dwordx4 v[44:45], v[48:51], off
	v_pk_fma_f32 v[36:37], v[36:37], v[96:97], v[40:41]
	s_nop 0
	v_cvt_pk_f16_f32 v40, v36, v37
	v_cvt_f32_f16_e32 v36, v154
	v_cvt_f32_f16_sdwa v37, v154 dst_sel:DWORD dst_unused:UNUSED_PAD src0_sel:WORD_1
	v_pk_fma_f32 v[32:33], v[32:33], v[88:89], v[36:37]
	s_nop 0
	v_cvt_pk_f16_f32 v42, v32, v33
	v_cvt_f32_f16_e32 v32, v153
	v_cvt_f32_f16_sdwa v33, v153 dst_sel:DWORD dst_unused:UNUSED_PAD src0_sel:WORD_1
	v_pk_fma_f32 v[32:33], v[38:39], v[98:99], v[32:33]
	s_nop 0
	v_cvt_pk_f16_f32 v41, v32, v33
	v_cvt_f32_f16_e32 v32, v155
	v_cvt_f32_f16_sdwa v33, v155 dst_sel:DWORD dst_unused:UNUSED_PAD src0_sel:WORD_1
	v_pk_fma_f32 v[32:33], v[34:35], v[90:91], v[32:33]
	s_nop 0
	v_cvt_pk_f16_f32 v43, v32, v33
	v_cvt_f32_f16_e32 v32, v148
	v_cvt_f32_f16_sdwa v33, v148 dst_sel:DWORD dst_unused:UNUSED_PAD src0_sel:WORD_1
	global_store_dwordx4 v[44:45], v[40:43], off offset:256
	v_pk_fma_f32 v[28:29], v[28:29], v[116:117], v[32:33]
	s_nop 0
	v_cvt_pk_f16_f32 v32, v28, v29
	v_cvt_f32_f16_e32 v28, v150
	v_cvt_f32_f16_sdwa v29, v150 dst_sel:DWORD dst_unused:UNUSED_PAD src0_sel:WORD_1
	v_pk_fma_f32 v[24:25], v[24:25], v[108:109], v[28:29]
	s_nop 0
	v_cvt_pk_f16_f32 v34, v24, v25
	v_cvt_f32_f16_e32 v24, v149
	v_cvt_f32_f16_sdwa v25, v149 dst_sel:DWORD dst_unused:UNUSED_PAD src0_sel:WORD_1
	v_pk_fma_f32 v[24:25], v[30:31], v[118:119], v[24:25]
	s_nop 0
	v_cvt_pk_f16_f32 v33, v24, v25
	v_cvt_f32_f16_e32 v24, v151
	v_cvt_f32_f16_sdwa v25, v151 dst_sel:DWORD dst_unused:UNUSED_PAD src0_sel:WORD_1
	v_pk_fma_f32 v[24:25], v[26:27], v[110:111], v[24:25]
	s_nop 0
	v_cvt_pk_f16_f32 v35, v24, v25
	v_lshl_add_u64 v[24:25], s[56:57], 0, v[224:225]
	v_lshl_add_u64 v[28:29], v[24:25], 0, v[220:221]
	v_cvt_f32_f16_e32 v24, v144
	v_cvt_f32_f16_sdwa v25, v144 dst_sel:DWORD dst_unused:UNUSED_PAD src0_sel:WORD_1
	global_store_dwordx4 v[28:29], v[32:35], off
	v_pk_fma_f32 v[20:21], v[20:21], v[96:97], v[24:25]
	s_nop 0
	v_cvt_pk_f16_f32 v24, v20, v21
	v_cvt_f32_f16_e32 v20, v146
	v_cvt_f32_f16_sdwa v21, v146 dst_sel:DWORD dst_unused:UNUSED_PAD src0_sel:WORD_1
	v_pk_fma_f32 v[16:17], v[16:17], v[88:89], v[20:21]
	s_nop 0
	v_cvt_pk_f16_f32 v26, v16, v17
	v_cvt_f32_f16_e32 v16, v145
	v_cvt_f32_f16_sdwa v17, v145 dst_sel:DWORD dst_unused:UNUSED_PAD src0_sel:WORD_1
	v_pk_fma_f32 v[16:17], v[22:23], v[98:99], v[16:17]
	s_nop 0
	v_cvt_pk_f16_f32 v25, v16, v17
	v_cvt_f32_f16_e32 v16, v147
	v_cvt_f32_f16_sdwa v17, v147 dst_sel:DWORD dst_unused:UNUSED_PAD src0_sel:WORD_1
	v_pk_fma_f32 v[16:17], v[18:19], v[90:91], v[16:17]
	s_nop 0
	v_cvt_pk_f16_f32 v27, v16, v17
	v_cvt_f32_f16_e32 v16, v136
	v_cvt_f32_f16_sdwa v17, v136 dst_sel:DWORD dst_unused:UNUSED_PAD src0_sel:WORD_1
	global_store_dwordx4 v[28:29], v[24:27], off offset:256
	v_pk_fma_f32 v[12:13], v[12:13], v[116:117], v[16:17]
	s_nop 0
	v_cvt_pk_f16_f32 v16, v12, v13
	v_cvt_f32_f16_e32 v12, v138
	v_cvt_f32_f16_sdwa v13, v138 dst_sel:DWORD dst_unused:UNUSED_PAD src0_sel:WORD_1
	v_pk_fma_f32 v[8:9], v[8:9], v[108:109], v[12:13]
	s_nop 0
	v_cvt_pk_f16_f32 v18, v8, v9
	v_cvt_f32_f16_e32 v8, v137
	v_cvt_f32_f16_sdwa v9, v137 dst_sel:DWORD dst_unused:UNUSED_PAD src0_sel:WORD_1
	v_pk_fma_f32 v[8:9], v[14:15], v[118:119], v[8:9]
	s_nop 0
	v_cvt_pk_f16_f32 v17, v8, v9
	v_cvt_f32_f16_e32 v8, v139
	v_cvt_f32_f16_sdwa v9, v139 dst_sel:DWORD dst_unused:UNUSED_PAD src0_sel:WORD_1
	v_pk_fma_f32 v[8:9], v[10:11], v[110:111], v[8:9]
	s_nop 0
	v_cvt_pk_f16_f32 v19, v8, v9
	v_lshl_add_u64 v[8:9], s[56:57], 0, v[222:223]
	v_lshl_add_u64 v[12:13], v[8:9], 0, v[220:221]
	v_cvt_f32_f16_e32 v8, v128
	v_cvt_f32_f16_sdwa v9, v128 dst_sel:DWORD dst_unused:UNUSED_PAD src0_sel:WORD_1
	global_store_dwordx4 v[12:13], v[16:19], off
	v_pk_fma_f32 v[4:5], v[4:5], v[96:97], v[8:9]
	s_nop 0
	v_cvt_pk_f16_f32 v8, v4, v5
	v_cvt_f32_f16_e32 v4, v130
	v_cvt_f32_f16_sdwa v5, v130 dst_sel:DWORD dst_unused:UNUSED_PAD src0_sel:WORD_1
	v_pk_fma_f32 v[0:1], v[0:1], v[88:89], v[4:5]
	s_nop 0
	v_cvt_pk_f16_f32 v10, v0, v1
	v_cvt_f32_f16_e32 v0, v129
	v_cvt_f32_f16_sdwa v1, v129 dst_sel:DWORD dst_unused:UNUSED_PAD src0_sel:WORD_1
	v_pk_fma_f32 v[0:1], v[6:7], v[98:99], v[0:1]
	s_nop 0
	v_cvt_pk_f16_f32 v9, v0, v1
	v_cvt_f32_f16_e32 v0, v131
	v_cvt_f32_f16_sdwa v1, v131 dst_sel:DWORD dst_unused:UNUSED_PAD src0_sel:WORD_1
	v_pk_fma_f32 v[0:1], v[2:3], v[90:91], v[0:1]
	s_nop 0
	v_cvt_pk_f16_f32 v11, v0, v1
	global_store_dwordx4 v[12:13], v[8:11], off offset:256
	s_cbranch_vccz .LBB0_1178
	s_waitcnt vmcnt(0)
	s_cmpk_gt_u32 s34, 0xff
	s_cbranch_scc1 .LBB0_1189
	s_barrier
